# scan: S state kept in the packed registers across the chunk loop (copies hoisted), constant lane masks for the last reduce stages
# speedup vs baseline: 1.0130x; 1.0057x over previous
; #define SCAN_BAR() asm volatile("s_barrier" ::: "memory")
; __device__ __forceinline__ void scan_unit(const Ctx& C0, const float* scn, int T, int quarter, const float* S0, float* Sout, unsigned char* obase, int mode) {
;     ...
;         float S0x = 0.f, S1x = 0.f, S2x = 0.f, S3x = 0.f;
;         if (S0) { const f32x4 t = *(const f32x4*)(S0 + irow * 64 + 4 * q); S0x = t.x; S1x = t.y; S2x = t.z; S3x = t.w; }
;         SCAN_BAR();
;         for (int k = 0; k < nch; ++k) {
;             const unsigned aq = (unsigned)(size_t)(C.lds + (k & 1) * SLOT_B) + 16u * (unsigned)q, av = (unsigned)(size_t)(C.lds + (k & 1) * SLOT_B) + (320u + (unsigned)irow) * 4u;
;             float osel0, osel1;
;             asm volatile(SCAN_CHUNK_ASM : "+v"(S0x), "+v"(S1x), "+v"(S2x), "+v"(S3x), "=&v"(osel0), "=&v"(osel1) : "v"(aq), "v"(av), "v"(q) : SCAN_CHUNK_CLOBBERS, "memory");
.LBB0_683:
	s_and_b64 vcc, exec, s[0:1]
	s_cbranch_vccz .LBB0_687
	v_lshrrev_b32_e32 v2, 4, v53
	s_lshl_b32 s1, s9, 2
	s_bfe_u32 s0, s72, 0x20003
	v_and_or_b32 v0, s1, 12, v2
	v_lshl_or_b32 v0, s0, 4, v0
	s_lshl_b32 s10, s2, 8
	s_lshl_b32 s0, s0, 6
	s_mul_i32 s9, s3, 0x5600000
	v_mov_b32_e32 v5, 0x500
	s_or_b32 s0, s10, s0
	s_mul_hi_i32 s1, s3, 0x5600000
	v_lshl_or_b32 v6, v0, 2, v5
	s_add_i32 s11, 0, 0xc000
	s_or_b32 s0, s9, s0
	s_waitcnt lgkmcnt(0)
	v_and_b32_e32 v3, 15, v52
	v_add_u32_e32 v9, 0, v6
	v_add_u32_e32 v11, s11, v6
	v_mov_b32_e32 v6, s0
	v_mov_b32_e32 v7, s1
	s_movk_i32 s0, 0x2b00
	v_mad_u64_u32 v[6:7], s[0:1], v3, s0, v[6:7]
	s_lshr_b32 s0, s8, 2
	s_and_b32 s0, s0, 48
	v_lshlrev_b32_e32 v2, 2, v2
	s_barrier
	v_or3_b32 v6, s0, v2, v6
	v_readlane_b32 s0, v253, 4
	v_lshlrev_b32_e32 v4, 4, v3
	v_readlane_b32 s1, v253, 5
	v_add_u32_e32 v5, 0, v4
	v_add_u32_e32 v10, s11, v4
	v_lshl_add_u64 v[6:7], s[0:1], 0, v[6:7]
	v_mov_b32_e32 v8, 0
	s_mov_b64 s[0:1], 0
	v_mov_b32_e32 v12, 0
	v_mov_b32_e32 v13, 0
	v_mov_b32_e32 v2, 0
	v_mov_b32_e32 v138, v2
	v_mov_b32_e32 v139, v13
	v_mov_b32_e32 v140, v12
	v_mov_b32_e32 v141, v8
.LBB0_685:
	ds_read_b128 v[164:167], v5 offset:0
	ds_read_b128 v[168:171], v5 offset:256
	ds_read_b128 v[172:175], v5 offset:512
	ds_read_b128 v[176:179], v5 offset:768
	ds_read_b128 v[180:183], v5 offset:1024
	ds_read_b32 v184, v9 offset:0
	ds_read_b128 v[186:189], v5 offset:1536
	ds_read_b128 v[190:193], v5 offset:1792
	ds_read_b128 v[194:197], v5 offset:2048
	ds_read_b128 v[198:201], v5 offset:2304
	ds_read_b128 v[202:205], v5 offset:2560
	ds_read_b32 v206, v9 offset:1536
	s_waitcnt lgkmcnt(0)
	v_pk_mul_f32 v[144:145], v[138:139], v[164:165]
	v_pk_fma_f32 v[144:145], v[140:141], v[166:167], v[144:145]
	v_add_f32 v146, v144, v145
	ds_read_b128 v[208:211], v5 offset:3072
	ds_read_b128 v[212:215], v5 offset:3328
	ds_read_b128 v[216:219], v5 offset:3584
	ds_read_b128 v[220:223], v5 offset:3840
	ds_read_b128 v[224:227], v5 offset:4096
	ds_read_b32 v228, v9 offset:3072
	v_add_f32_dpp v146, v146, v146 quad_perm:[1,0,3,2] row_mask:0xf bank_mask:0xf bound_ctrl:1
	s_nop 0
	s_nop 0
	v_add_f32_dpp v146, v146, v146 quad_perm:[2,3,0,1] row_mask:0xf bank_mask:0xf bound_ctrl:1
	s_nop 0
	v_pk_mul_f32 v[176:177], v[176:177], v[184:185] op_sel_hi:[1,0]
	v_add_f32_dpp v146, v146, v146 row_half_mirror row_mask:0xf bank_mask:0xf bound_ctrl:1
	v_pk_mul_f32 v[178:179], v[178:179], v[184:185] op_sel_hi:[1,0]
	s_waitcnt lgkmcnt(6)
	v_add_f32_dpp v146, v146, v146 row_mirror row_mask:0xf bank_mask:0xf bound_ctrl:1
	v_pk_fma_f32 v[176:177], v[146:147], v[168:169], v[176:177] op_sel_hi:[0,1,1] neg_lo:[1,0,0] neg_hi:[1,0,0]
	v_pk_fma_f32 v[178:179], v[146:147], v[170:171], v[178:179] op_sel_hi:[0,1,1] neg_lo:[1,0,0] neg_hi:[1,0,0]
	v_pk_fma_f32 v[138:139], v[138:139], v[172:173], v[176:177]
	v_pk_fma_f32 v[140:141], v[140:141], v[174:175], v[178:179]
	v_pk_mul_f32 v[144:145], v[138:139], v[186:187]
	v_pk_fma_f32 v[144:145], v[140:141], v[188:189], v[144:145]
	v_add_f32 v146, v144, v145
	ds_read_b128 v[230:233], v5 offset:4608
	ds_read_b128 v[234:237], v5 offset:4864
	ds_read_b128 v[238:241], v5 offset:5120
	ds_read_b128 v[242:245], v5 offset:5376
	ds_read_b128 v[246:249], v5 offset:5632
	ds_read_b32 v250, v9 offset:4608
	v_add_f32_dpp v146, v146, v146 quad_perm:[1,0,3,2] row_mask:0xf bank_mask:0xf bound_ctrl:1
	v_pk_mul_f32 v[180:181], v[138:139], v[180:181]
	v_pk_fma_f32 v[180:181], v[140:141], v[182:183], v[180:181]
	v_add_f32_dpp v146, v146, v146 quad_perm:[2,3,0,1] row_mask:0xf bank_mask:0xf bound_ctrl:1
	v_add_f32 v148, v180, v181
	v_pk_mul_f32 v[198:199], v[198:199], v[206:207] op_sel_hi:[1,0]
	v_add_f32_dpp v146, v146, v146 row_half_mirror row_mask:0xf bank_mask:0xf bound_ctrl:1
	v_pk_mul_f32 v[200:201], v[200:201], v[206:207] op_sel_hi:[1,0]
	s_waitcnt lgkmcnt(6)
	v_add_f32_dpp v146, v146, v146 row_mirror row_mask:0xf bank_mask:0xf bound_ctrl:1
	v_pk_fma_f32 v[198:199], v[146:147], v[190:191], v[198:199] op_sel_hi:[0,1,1] neg_lo:[1,0,0] neg_hi:[1,0,0]
	v_pk_fma_f32 v[200:201], v[146:147], v[192:193], v[200:201] op_sel_hi:[0,1,1] neg_lo:[1,0,0] neg_hi:[1,0,0]
	v_pk_fma_f32 v[138:139], v[138:139], v[194:195], v[198:199]
	v_pk_fma_f32 v[140:141], v[140:141], v[196:197], v[200:201]
	v_pk_mul_f32 v[144:145], v[138:139], v[208:209]
	v_pk_fma_f32 v[144:145], v[140:141], v[210:211], v[144:145]
	v_add_f32 v146, v144, v145
	ds_read_b128 v[164:167], v5 offset:6144
	ds_read_b128 v[168:171], v5 offset:6400
	ds_read_b128 v[172:175], v5 offset:6656
	ds_read_b128 v[176:179], v5 offset:6912
	ds_read_b128 v[180:183], v5 offset:7168
	ds_read_b32 v184, v9 offset:6144
	v_add_f32_dpp v146, v146, v146 quad_perm:[1,0,3,2] row_mask:0xf bank_mask:0xf bound_ctrl:1
	v_pk_mul_f32 v[202:203], v[138:139], v[202:203]
	v_pk_fma_f32 v[202:203], v[140:141], v[204:205], v[202:203]
	v_add_f32_dpp v146, v146, v146 quad_perm:[2,3,0,1] row_mask:0xf bank_mask:0xf bound_ctrl:1
	v_add_f32 v149, v202, v203
	v_pk_mul_f32 v[220:221], v[220:221], v[228:229] op_sel_hi:[1,0]
	v_add_f32_dpp v146, v146, v146 row_half_mirror row_mask:0xf bank_mask:0xf bound_ctrl:1
	v_pk_mul_f32 v[222:223], v[222:223], v[228:229] op_sel_hi:[1,0]
	s_waitcnt lgkmcnt(6)
	v_add_f32_dpp v146, v146, v146 row_mirror row_mask:0xf bank_mask:0xf bound_ctrl:1
	v_pk_fma_f32 v[220:221], v[146:147], v[212:213], v[220:221] op_sel_hi:[0,1,1] neg_lo:[1,0,0] neg_hi:[1,0,0]
	v_pk_fma_f32 v[222:223], v[146:147], v[214:215], v[222:223] op_sel_hi:[0,1,1] neg_lo:[1,0,0] neg_hi:[1,0,0]
	v_pk_fma_f32 v[138:139], v[138:139], v[216:217], v[220:221]
	v_pk_fma_f32 v[140:141], v[140:141], v[218:219], v[222:223]
	v_pk_mul_f32 v[144:145], v[138:139], v[230:231]
	v_pk_fma_f32 v[144:145], v[140:141], v[232:233], v[144:145]
	v_add_f32 v146, v144, v145
	ds_read_b128 v[186:189], v5 offset:7680
	ds_read_b128 v[190:193], v5 offset:7936
	ds_read_b128 v[194:197], v5 offset:8192
	ds_read_b128 v[198:201], v5 offset:8448
	ds_read_b128 v[202:205], v5 offset:8704
	ds_read_b32 v206, v9 offset:7680
	v_add_f32_dpp v146, v146, v146 quad_perm:[1,0,3,2] row_mask:0xf bank_mask:0xf bound_ctrl:1
	v_pk_mul_f32 v[224:225], v[138:139], v[224:225]
	v_pk_fma_f32 v[224:225], v[140:141], v[226:227], v[224:225]
	v_add_f32_dpp v146, v146, v146 quad_perm:[2,3,0,1] row_mask:0xf bank_mask:0xf bound_ctrl:1
	v_add_f32 v150, v224, v225
	v_pk_mul_f32 v[242:243], v[242:243], v[250:251] op_sel_hi:[1,0]
	v_add_f32_dpp v146, v146, v146 row_half_mirror row_mask:0xf bank_mask:0xf bound_ctrl:1
	v_pk_mul_f32 v[244:245], v[244:245], v[250:251] op_sel_hi:[1,0]
	s_waitcnt lgkmcnt(6)
	v_add_f32_dpp v146, v146, v146 row_mirror row_mask:0xf bank_mask:0xf bound_ctrl:1
	v_pk_fma_f32 v[242:243], v[146:147], v[234:235], v[242:243] op_sel_hi:[0,1,1] neg_lo:[1,0,0] neg_hi:[1,0,0]
	v_pk_fma_f32 v[244:245], v[146:147], v[236:237], v[244:245] op_sel_hi:[0,1,1] neg_lo:[1,0,0] neg_hi:[1,0,0]
	v_pk_fma_f32 v[138:139], v[138:139], v[238:239], v[242:243]
	v_pk_fma_f32 v[140:141], v[140:141], v[240:241], v[244:245]
	v_pk_mul_f32 v[144:145], v[138:139], v[164:165]
	v_pk_fma_f32 v[144:145], v[140:141], v[166:167], v[144:145]
	v_add_f32 v146, v144, v145
	ds_read_b128 v[208:211], v5 offset:9216
	ds_read_b128 v[212:215], v5 offset:9472
	ds_read_b128 v[216:219], v5 offset:9728
	ds_read_b128 v[220:223], v5 offset:9984
	ds_read_b128 v[224:227], v5 offset:10240
	ds_read_b32 v228, v9 offset:9216
	v_add_f32_dpp v146, v146, v146 quad_perm:[1,0,3,2] row_mask:0xf bank_mask:0xf bound_ctrl:1
	v_pk_mul_f32 v[246:247], v[138:139], v[246:247]
	v_pk_fma_f32 v[246:247], v[140:141], v[248:249], v[246:247]
	v_add_f32_dpp v146, v146, v146 quad_perm:[2,3,0,1] row_mask:0xf bank_mask:0xf bound_ctrl:1
	v_add_f32 v151, v246, v247
	v_pk_mul_f32 v[176:177], v[176:177], v[184:185] op_sel_hi:[1,0]
	v_add_f32_dpp v146, v146, v146 row_half_mirror row_mask:0xf bank_mask:0xf bound_ctrl:1
	v_pk_mul_f32 v[178:179], v[178:179], v[184:185] op_sel_hi:[1,0]
	s_waitcnt lgkmcnt(6)
	v_add_f32_dpp v146, v146, v146 row_mirror row_mask:0xf bank_mask:0xf bound_ctrl:1
	v_pk_fma_f32 v[176:177], v[146:147], v[168:169], v[176:177] op_sel_hi:[0,1,1] neg_lo:[1,0,0] neg_hi:[1,0,0]
	v_pk_fma_f32 v[178:179], v[146:147], v[170:171], v[178:179] op_sel_hi:[0,1,1] neg_lo:[1,0,0] neg_hi:[1,0,0]
	v_pk_fma_f32 v[138:139], v[138:139], v[172:173], v[176:177]
	v_pk_fma_f32 v[140:141], v[140:141], v[174:175], v[178:179]
	v_pk_mul_f32 v[144:145], v[138:139], v[186:187]
	v_pk_fma_f32 v[144:145], v[140:141], v[188:189], v[144:145]
	v_add_f32 v146, v144, v145
	ds_read_b128 v[230:233], v5 offset:10752
	ds_read_b128 v[234:237], v5 offset:11008
	ds_read_b128 v[238:241], v5 offset:11264
	ds_read_b128 v[242:245], v5 offset:11520
	ds_read_b128 v[246:249], v5 offset:11776
	ds_read_b32 v250, v9 offset:10752
	v_add_f32_dpp v146, v146, v146 quad_perm:[1,0,3,2] row_mask:0xf bank_mask:0xf bound_ctrl:1
	v_pk_mul_f32 v[180:181], v[138:139], v[180:181]
	v_pk_fma_f32 v[180:181], v[140:141], v[182:183], v[180:181]
	v_add_f32_dpp v146, v146, v146 quad_perm:[2,3,0,1] row_mask:0xf bank_mask:0xf bound_ctrl:1
	v_add_f32 v152, v180, v181
	v_pk_mul_f32 v[198:199], v[198:199], v[206:207] op_sel_hi:[1,0]
	v_add_f32_dpp v146, v146, v146 row_half_mirror row_mask:0xf bank_mask:0xf bound_ctrl:1
	v_pk_mul_f32 v[200:201], v[200:201], v[206:207] op_sel_hi:[1,0]
	s_waitcnt lgkmcnt(6)
	v_add_f32_dpp v146, v146, v146 row_mirror row_mask:0xf bank_mask:0xf bound_ctrl:1
	v_pk_fma_f32 v[198:199], v[146:147], v[190:191], v[198:199] op_sel_hi:[0,1,1] neg_lo:[1,0,0] neg_hi:[1,0,0]
	v_pk_fma_f32 v[200:201], v[146:147], v[192:193], v[200:201] op_sel_hi:[0,1,1] neg_lo:[1,0,0] neg_hi:[1,0,0]
	v_pk_fma_f32 v[138:139], v[138:139], v[194:195], v[198:199]
	v_pk_fma_f32 v[140:141], v[140:141], v[196:197], v[200:201]
	v_pk_mul_f32 v[144:145], v[138:139], v[208:209]
	v_pk_fma_f32 v[144:145], v[140:141], v[210:211], v[144:145]
	v_add_f32 v146, v144, v145
	ds_read_b128 v[164:167], v5 offset:12288
	ds_read_b128 v[168:171], v5 offset:12544
	ds_read_b128 v[172:175], v5 offset:12800
	ds_read_b128 v[176:179], v5 offset:13056
	ds_read_b128 v[180:183], v5 offset:13312
	ds_read_b32 v184, v9 offset:12288
	v_add_f32_dpp v146, v146, v146 quad_perm:[1,0,3,2] row_mask:0xf bank_mask:0xf bound_ctrl:1
	v_pk_mul_f32 v[202:203], v[138:139], v[202:203]
	v_pk_fma_f32 v[202:203], v[140:141], v[204:205], v[202:203]
	v_add_f32_dpp v146, v146, v146 quad_perm:[2,3,0,1] row_mask:0xf bank_mask:0xf bound_ctrl:1
	v_add_f32 v153, v202, v203
	v_pk_mul_f32 v[220:221], v[220:221], v[228:229] op_sel_hi:[1,0]
	v_add_f32_dpp v146, v146, v146 row_half_mirror row_mask:0xf bank_mask:0xf bound_ctrl:1
	v_pk_mul_f32 v[222:223], v[222:223], v[228:229] op_sel_hi:[1,0]
	s_waitcnt lgkmcnt(6)
	v_add_f32_dpp v146, v146, v146 row_mirror row_mask:0xf bank_mask:0xf bound_ctrl:1
	v_pk_fma_f32 v[220:221], v[146:147], v[212:213], v[220:221] op_sel_hi:[0,1,1] neg_lo:[1,0,0] neg_hi:[1,0,0]
	v_pk_fma_f32 v[222:223], v[146:147], v[214:215], v[222:223] op_sel_hi:[0,1,1] neg_lo:[1,0,0] neg_hi:[1,0,0]
	v_pk_fma_f32 v[138:139], v[138:139], v[216:217], v[220:221]
	v_pk_fma_f32 v[140:141], v[140:141], v[218:219], v[222:223]
	v_pk_mul_f32 v[144:145], v[138:139], v[230:231]
	v_pk_fma_f32 v[144:145], v[140:141], v[232:233], v[144:145]
	v_add_f32 v146, v144, v145
	ds_read_b128 v[186:189], v5 offset:13824
	ds_read_b128 v[190:193], v5 offset:14080
	ds_read_b128 v[194:197], v5 offset:14336
	ds_read_b128 v[198:201], v5 offset:14592
	ds_read_b128 v[202:205], v5 offset:14848
	ds_read_b32 v206, v9 offset:13824
	v_add_f32_dpp v146, v146, v146 quad_perm:[1,0,3,2] row_mask:0xf bank_mask:0xf bound_ctrl:1
	v_pk_mul_f32 v[224:225], v[138:139], v[224:225]
	v_pk_fma_f32 v[224:225], v[140:141], v[226:227], v[224:225]
	v_add_f32_dpp v146, v146, v146 quad_perm:[2,3,0,1] row_mask:0xf bank_mask:0xf bound_ctrl:1
	v_add_f32 v154, v224, v225
	v_pk_mul_f32 v[242:243], v[242:243], v[250:251] op_sel_hi:[1,0]
	v_add_f32_dpp v146, v146, v146 row_half_mirror row_mask:0xf bank_mask:0xf bound_ctrl:1
	v_pk_mul_f32 v[244:245], v[244:245], v[250:251] op_sel_hi:[1,0]
	s_waitcnt lgkmcnt(6)
	v_add_f32_dpp v146, v146, v146 row_mirror row_mask:0xf bank_mask:0xf bound_ctrl:1
	v_pk_fma_f32 v[242:243], v[146:147], v[234:235], v[242:243] op_sel_hi:[0,1,1] neg_lo:[1,0,0] neg_hi:[1,0,0]
	v_pk_fma_f32 v[244:245], v[146:147], v[236:237], v[244:245] op_sel_hi:[0,1,1] neg_lo:[1,0,0] neg_hi:[1,0,0]
	v_pk_fma_f32 v[138:139], v[138:139], v[238:239], v[242:243]
	v_pk_fma_f32 v[140:141], v[140:141], v[240:241], v[244:245]
	v_pk_mul_f32 v[144:145], v[138:139], v[164:165]
	v_pk_fma_f32 v[144:145], v[140:141], v[166:167], v[144:145]
	v_add_f32 v146, v144, v145
	ds_read_b128 v[208:211], v5 offset:15360
	ds_read_b128 v[212:215], v5 offset:15616
	ds_read_b128 v[216:219], v5 offset:15872
	ds_read_b128 v[220:223], v5 offset:16128
	ds_read_b128 v[224:227], v5 offset:16384
	ds_read_b32 v228, v9 offset:15360
	v_add_f32_dpp v146, v146, v146 quad_perm:[1,0,3,2] row_mask:0xf bank_mask:0xf bound_ctrl:1
	v_pk_mul_f32 v[246:247], v[138:139], v[246:247]
	v_pk_fma_f32 v[246:247], v[140:141], v[248:249], v[246:247]
	v_add_f32_dpp v146, v146, v146 quad_perm:[2,3,0,1] row_mask:0xf bank_mask:0xf bound_ctrl:1
	v_add_f32 v155, v246, v247
	v_pk_mul_f32 v[176:177], v[176:177], v[184:185] op_sel_hi:[1,0]
	v_add_f32_dpp v146, v146, v146 row_half_mirror row_mask:0xf bank_mask:0xf bound_ctrl:1
	v_pk_mul_f32 v[178:179], v[178:179], v[184:185] op_sel_hi:[1,0]
	s_waitcnt lgkmcnt(6)
	v_add_f32_dpp v146, v146, v146 row_mirror row_mask:0xf bank_mask:0xf bound_ctrl:1
	v_pk_fma_f32 v[176:177], v[146:147], v[168:169], v[176:177] op_sel_hi:[0,1,1] neg_lo:[1,0,0] neg_hi:[1,0,0]
	v_pk_fma_f32 v[178:179], v[146:147], v[170:171], v[178:179] op_sel_hi:[0,1,1] neg_lo:[1,0,0] neg_hi:[1,0,0]
	v_pk_fma_f32 v[138:139], v[138:139], v[172:173], v[176:177]
	v_pk_fma_f32 v[140:141], v[140:141], v[174:175], v[178:179]
	v_pk_mul_f32 v[144:145], v[138:139], v[186:187]
	v_pk_fma_f32 v[144:145], v[140:141], v[188:189], v[144:145]
	v_add_f32 v146, v144, v145
	ds_read_b128 v[230:233], v5 offset:16896
	ds_read_b128 v[234:237], v5 offset:17152
	ds_read_b128 v[238:241], v5 offset:17408
	ds_read_b128 v[242:245], v5 offset:17664
	ds_read_b128 v[246:249], v5 offset:17920
	ds_read_b32 v250, v9 offset:16896
	v_add_f32_dpp v146, v146, v146 quad_perm:[1,0,3,2] row_mask:0xf bank_mask:0xf bound_ctrl:1
	v_pk_mul_f32 v[180:181], v[138:139], v[180:181]
	v_pk_fma_f32 v[180:181], v[140:141], v[182:183], v[180:181]
	v_add_f32_dpp v146, v146, v146 quad_perm:[2,3,0,1] row_mask:0xf bank_mask:0xf bound_ctrl:1
	v_add_f32 v156, v180, v181
	v_pk_mul_f32 v[198:199], v[198:199], v[206:207] op_sel_hi:[1,0]
	v_add_f32_dpp v146, v146, v146 row_half_mirror row_mask:0xf bank_mask:0xf bound_ctrl:1
	v_pk_mul_f32 v[200:201], v[200:201], v[206:207] op_sel_hi:[1,0]
	s_waitcnt lgkmcnt(6)
	v_add_f32_dpp v146, v146, v146 row_mirror row_mask:0xf bank_mask:0xf bound_ctrl:1
	v_pk_fma_f32 v[198:199], v[146:147], v[190:191], v[198:199] op_sel_hi:[0,1,1] neg_lo:[1,0,0] neg_hi:[1,0,0]
	v_pk_fma_f32 v[200:201], v[146:147], v[192:193], v[200:201] op_sel_hi:[0,1,1] neg_lo:[1,0,0] neg_hi:[1,0,0]
	v_pk_fma_f32 v[138:139], v[138:139], v[194:195], v[198:199]
	v_pk_fma_f32 v[140:141], v[140:141], v[196:197], v[200:201]
	v_pk_mul_f32 v[144:145], v[138:139], v[208:209]
	v_pk_fma_f32 v[144:145], v[140:141], v[210:211], v[144:145]
	v_add_f32 v146, v144, v145
	ds_read_b128 v[164:167], v5 offset:18432
	ds_read_b128 v[168:171], v5 offset:18688
	ds_read_b128 v[172:175], v5 offset:18944
	ds_read_b128 v[176:179], v5 offset:19200
	ds_read_b128 v[180:183], v5 offset:19456
	ds_read_b32 v184, v9 offset:18432
	v_add_f32_dpp v146, v146, v146 quad_perm:[1,0,3,2] row_mask:0xf bank_mask:0xf bound_ctrl:1
	v_pk_mul_f32 v[202:203], v[138:139], v[202:203]
	v_pk_fma_f32 v[202:203], v[140:141], v[204:205], v[202:203]
	v_add_f32_dpp v146, v146, v146 quad_perm:[2,3,0,1] row_mask:0xf bank_mask:0xf bound_ctrl:1
	v_add_f32 v157, v202, v203
	v_pk_mul_f32 v[220:221], v[220:221], v[228:229] op_sel_hi:[1,0]
	v_add_f32_dpp v146, v146, v146 row_half_mirror row_mask:0xf bank_mask:0xf bound_ctrl:1
	v_pk_mul_f32 v[222:223], v[222:223], v[228:229] op_sel_hi:[1,0]
	s_waitcnt lgkmcnt(6)
	v_add_f32_dpp v146, v146, v146 row_mirror row_mask:0xf bank_mask:0xf bound_ctrl:1
	v_pk_fma_f32 v[220:221], v[146:147], v[212:213], v[220:221] op_sel_hi:[0,1,1] neg_lo:[1,0,0] neg_hi:[1,0,0]
	v_pk_fma_f32 v[222:223], v[146:147], v[214:215], v[222:223] op_sel_hi:[0,1,1] neg_lo:[1,0,0] neg_hi:[1,0,0]
	v_pk_fma_f32 v[138:139], v[138:139], v[216:217], v[220:221]
	v_pk_fma_f32 v[140:141], v[140:141], v[218:219], v[222:223]
	v_pk_mul_f32 v[144:145], v[138:139], v[230:231]
	v_pk_fma_f32 v[144:145], v[140:141], v[232:233], v[144:145]
	v_add_f32 v146, v144, v145
	ds_read_b128 v[186:189], v5 offset:19968
	ds_read_b128 v[190:193], v5 offset:20224
	ds_read_b128 v[194:197], v5 offset:20480
	ds_read_b128 v[198:201], v5 offset:20736
	ds_read_b128 v[202:205], v5 offset:20992
	ds_read_b32 v206, v9 offset:19968
	v_add_f32_dpp v146, v146, v146 quad_perm:[1,0,3,2] row_mask:0xf bank_mask:0xf bound_ctrl:1
	v_pk_mul_f32 v[224:225], v[138:139], v[224:225]
	v_pk_fma_f32 v[224:225], v[140:141], v[226:227], v[224:225]
	v_add_f32_dpp v146, v146, v146 quad_perm:[2,3,0,1] row_mask:0xf bank_mask:0xf bound_ctrl:1
	v_add_f32 v158, v224, v225
	v_pk_mul_f32 v[242:243], v[242:243], v[250:251] op_sel_hi:[1,0]
	v_add_f32_dpp v146, v146, v146 row_half_mirror row_mask:0xf bank_mask:0xf bound_ctrl:1
	v_pk_mul_f32 v[244:245], v[244:245], v[250:251] op_sel_hi:[1,0]
	s_waitcnt lgkmcnt(6)
	v_add_f32_dpp v146, v146, v146 row_mirror row_mask:0xf bank_mask:0xf bound_ctrl:1
	v_pk_fma_f32 v[242:243], v[146:147], v[234:235], v[242:243] op_sel_hi:[0,1,1] neg_lo:[1,0,0] neg_hi:[1,0,0]
	v_pk_fma_f32 v[244:245], v[146:147], v[236:237], v[244:245] op_sel_hi:[0,1,1] neg_lo:[1,0,0] neg_hi:[1,0,0]
	v_pk_fma_f32 v[138:139], v[138:139], v[238:239], v[242:243]
	v_pk_fma_f32 v[140:141], v[140:141], v[240:241], v[244:245]
	v_pk_mul_f32 v[144:145], v[138:139], v[164:165]
	v_pk_fma_f32 v[144:145], v[140:141], v[166:167], v[144:145]
	v_add_f32 v146, v144, v145
	ds_read_b128 v[208:211], v5 offset:21504
	ds_read_b128 v[212:215], v5 offset:21760
	ds_read_b128 v[216:219], v5 offset:22016
	ds_read_b128 v[220:223], v5 offset:22272
	ds_read_b128 v[224:227], v5 offset:22528
	ds_read_b32 v228, v9 offset:21504
	v_add_f32_dpp v146, v146, v146 quad_perm:[1,0,3,2] row_mask:0xf bank_mask:0xf bound_ctrl:1
	v_pk_mul_f32 v[246:247], v[138:139], v[246:247]
	v_pk_fma_f32 v[246:247], v[140:141], v[248:249], v[246:247]
	v_add_f32_dpp v146, v146, v146 quad_perm:[2,3,0,1] row_mask:0xf bank_mask:0xf bound_ctrl:1
	v_add_f32 v159, v246, v247
	v_pk_mul_f32 v[176:177], v[176:177], v[184:185] op_sel_hi:[1,0]
	v_add_f32_dpp v146, v146, v146 row_half_mirror row_mask:0xf bank_mask:0xf bound_ctrl:1
	v_pk_mul_f32 v[178:179], v[178:179], v[184:185] op_sel_hi:[1,0]
	s_waitcnt lgkmcnt(6)
	v_add_f32_dpp v146, v146, v146 row_mirror row_mask:0xf bank_mask:0xf bound_ctrl:1
	v_pk_fma_f32 v[176:177], v[146:147], v[168:169], v[176:177] op_sel_hi:[0,1,1] neg_lo:[1,0,0] neg_hi:[1,0,0]
	v_pk_fma_f32 v[178:179], v[146:147], v[170:171], v[178:179] op_sel_hi:[0,1,1] neg_lo:[1,0,0] neg_hi:[1,0,0]
	v_pk_fma_f32 v[138:139], v[138:139], v[172:173], v[176:177]
	v_pk_fma_f32 v[140:141], v[140:141], v[174:175], v[178:179]
	v_pk_mul_f32 v[144:145], v[138:139], v[186:187]
	v_pk_fma_f32 v[144:145], v[140:141], v[188:189], v[144:145]
	v_add_f32 v146, v144, v145
	ds_read_b128 v[230:233], v5 offset:23040
	ds_read_b128 v[234:237], v5 offset:23296
	ds_read_b128 v[238:241], v5 offset:23552
	ds_read_b128 v[242:245], v5 offset:23808
	ds_read_b128 v[246:249], v5 offset:24064
	ds_read_b32 v250, v9 offset:23040
	v_add_f32_dpp v146, v146, v146 quad_perm:[1,0,3,2] row_mask:0xf bank_mask:0xf bound_ctrl:1
	v_pk_mul_f32 v[180:181], v[138:139], v[180:181]
	v_pk_fma_f32 v[180:181], v[140:141], v[182:183], v[180:181]
	v_add_f32_dpp v146, v146, v146 quad_perm:[2,3,0,1] row_mask:0xf bank_mask:0xf bound_ctrl:1
	v_add_f32 v160, v180, v181
	v_pk_mul_f32 v[198:199], v[198:199], v[206:207] op_sel_hi:[1,0]
	v_add_f32_dpp v146, v146, v146 row_half_mirror row_mask:0xf bank_mask:0xf bound_ctrl:1
	v_pk_mul_f32 v[200:201], v[200:201], v[206:207] op_sel_hi:[1,0]
	s_waitcnt lgkmcnt(6)
	v_add_f32_dpp v146, v146, v146 row_mirror row_mask:0xf bank_mask:0xf bound_ctrl:1
	v_pk_fma_f32 v[198:199], v[146:147], v[190:191], v[198:199] op_sel_hi:[0,1,1] neg_lo:[1,0,0] neg_hi:[1,0,0]
	v_pk_fma_f32 v[200:201], v[146:147], v[192:193], v[200:201] op_sel_hi:[0,1,1] neg_lo:[1,0,0] neg_hi:[1,0,0]
	v_pk_fma_f32 v[138:139], v[138:139], v[194:195], v[198:199]
	v_pk_fma_f32 v[140:141], v[140:141], v[196:197], v[200:201]
	v_pk_mul_f32 v[144:145], v[138:139], v[208:209]
	v_pk_fma_f32 v[144:145], v[140:141], v[210:211], v[144:145]
	v_add_f32 v146, v144, v145
	ds_read_b128 v[164:167], v5 offset:24576
	ds_read_b128 v[168:171], v5 offset:24832
	ds_read_b128 v[172:175], v5 offset:25088
	ds_read_b128 v[176:179], v5 offset:25344
	ds_read_b128 v[180:183], v5 offset:25600
	ds_read_b32 v184, v9 offset:24576
	v_add_f32_dpp v146, v146, v146 quad_perm:[1,0,3,2] row_mask:0xf bank_mask:0xf bound_ctrl:1
	v_pk_mul_f32 v[202:203], v[138:139], v[202:203]
	v_pk_fma_f32 v[202:203], v[140:141], v[204:205], v[202:203]
	v_add_f32_dpp v146, v146, v146 quad_perm:[2,3,0,1] row_mask:0xf bank_mask:0xf bound_ctrl:1
	v_add_f32 v161, v202, v203
	v_pk_mul_f32 v[220:221], v[220:221], v[228:229] op_sel_hi:[1,0]
	v_add_f32_dpp v146, v146, v146 row_half_mirror row_mask:0xf bank_mask:0xf bound_ctrl:1
	v_pk_mul_f32 v[222:223], v[222:223], v[228:229] op_sel_hi:[1,0]
	s_waitcnt lgkmcnt(6)
	v_add_f32_dpp v146, v146, v146 row_mirror row_mask:0xf bank_mask:0xf bound_ctrl:1
	v_pk_fma_f32 v[220:221], v[146:147], v[212:213], v[220:221] op_sel_hi:[0,1,1] neg_lo:[1,0,0] neg_hi:[1,0,0]
	v_pk_fma_f32 v[222:223], v[146:147], v[214:215], v[222:223] op_sel_hi:[0,1,1] neg_lo:[1,0,0] neg_hi:[1,0,0]
	v_pk_fma_f32 v[138:139], v[138:139], v[216:217], v[220:221]
	v_pk_fma_f32 v[140:141], v[140:141], v[218:219], v[222:223]
	v_pk_mul_f32 v[144:145], v[138:139], v[230:231]
	v_pk_fma_f32 v[144:145], v[140:141], v[232:233], v[144:145]
	v_add_f32 v146, v144, v145
	ds_read_b128 v[186:189], v5 offset:26112
	ds_read_b128 v[190:193], v5 offset:26368
	ds_read_b128 v[194:197], v5 offset:26624
	ds_read_b128 v[198:201], v5 offset:26880
	ds_read_b128 v[202:205], v5 offset:27136
	ds_read_b32 v206, v9 offset:26112
	v_add_f32_dpp v146, v146, v146 quad_perm:[1,0,3,2] row_mask:0xf bank_mask:0xf bound_ctrl:1
	v_pk_mul_f32 v[224:225], v[138:139], v[224:225]
	v_pk_fma_f32 v[224:225], v[140:141], v[226:227], v[224:225]
	v_add_f32_dpp v146, v146, v146 quad_perm:[2,3,0,1] row_mask:0xf bank_mask:0xf bound_ctrl:1
	v_add_f32 v162, v224, v225
	v_pk_mul_f32 v[242:243], v[242:243], v[250:251] op_sel_hi:[1,0]
	v_add_f32_dpp v146, v146, v146 row_half_mirror row_mask:0xf bank_mask:0xf bound_ctrl:1
	v_pk_mul_f32 v[244:245], v[244:245], v[250:251] op_sel_hi:[1,0]
	s_waitcnt lgkmcnt(6)
	v_add_f32_dpp v146, v146, v146 row_mirror row_mask:0xf bank_mask:0xf bound_ctrl:1
	v_pk_fma_f32 v[242:243], v[146:147], v[234:235], v[242:243] op_sel_hi:[0,1,1] neg_lo:[1,0,0] neg_hi:[1,0,0]
	v_pk_fma_f32 v[244:245], v[146:147], v[236:237], v[244:245] op_sel_hi:[0,1,1] neg_lo:[1,0,0] neg_hi:[1,0,0]
	v_pk_fma_f32 v[138:139], v[138:139], v[238:239], v[242:243]
	v_pk_fma_f32 v[140:141], v[140:141], v[240:241], v[244:245]
	v_pk_mul_f32 v[144:145], v[138:139], v[164:165]
	v_pk_fma_f32 v[144:145], v[140:141], v[166:167], v[144:145]
	v_add_f32 v146, v144, v145
	ds_read_b128 v[208:211], v5 offset:27648
	ds_read_b128 v[212:215], v5 offset:27904
	ds_read_b128 v[216:219], v5 offset:28160
	ds_read_b128 v[220:223], v5 offset:28416
	ds_read_b128 v[224:227], v5 offset:28672
	ds_read_b32 v228, v9 offset:27648
	v_add_f32_dpp v146, v146, v146 quad_perm:[1,0,3,2] row_mask:0xf bank_mask:0xf bound_ctrl:1
	v_pk_mul_f32 v[246:247], v[138:139], v[246:247]
	v_pk_fma_f32 v[246:247], v[140:141], v[248:249], v[246:247]
	v_add_f32_dpp v146, v146, v146 quad_perm:[2,3,0,1] row_mask:0xf bank_mask:0xf bound_ctrl:1
	v_add_f32 v163, v246, v247
	v_pk_mul_f32 v[176:177], v[176:177], v[184:185] op_sel_hi:[1,0]
	v_add_f32_dpp v146, v146, v146 row_half_mirror row_mask:0xf bank_mask:0xf bound_ctrl:1
	v_pk_mul_f32 v[178:179], v[178:179], v[184:185] op_sel_hi:[1,0]
	s_waitcnt lgkmcnt(6)
	v_add_f32_dpp v146, v146, v146 row_mirror row_mask:0xf bank_mask:0xf bound_ctrl:1
	v_pk_fma_f32 v[176:177], v[146:147], v[168:169], v[176:177] op_sel_hi:[0,1,1] neg_lo:[1,0,0] neg_hi:[1,0,0]
	v_pk_fma_f32 v[178:179], v[146:147], v[170:171], v[178:179] op_sel_hi:[0,1,1] neg_lo:[1,0,0] neg_hi:[1,0,0]
	v_pk_fma_f32 v[138:139], v[138:139], v[172:173], v[176:177]
	v_pk_fma_f32 v[140:141], v[140:141], v[174:175], v[178:179]
	v_pk_mul_f32 v[144:145], v[138:139], v[186:187]
	v_pk_fma_f32 v[144:145], v[140:141], v[188:189], v[144:145]
	v_add_f32 v146, v144, v145
	v_add_f32_dpp v230, v148, v148 row_mirror row_mask:0xf bank_mask:0x3 bound_ctrl:1
	v_add_f32_dpp v230, v156, v156 row_mirror row_mask:0xf bank_mask:0xc bound_ctrl:1
	v_add_f32_dpp v231, v149, v149 row_mirror row_mask:0xf bank_mask:0x3 bound_ctrl:1
	v_add_f32_dpp v231, v157, v157 row_mirror row_mask:0xf bank_mask:0xc bound_ctrl:1
	v_add_f32_dpp v232, v150, v150 row_mirror row_mask:0xf bank_mask:0x3 bound_ctrl:1
	v_add_f32_dpp v232, v158, v158 row_mirror row_mask:0xf bank_mask:0xc bound_ctrl:1
	v_add_f32_dpp v233, v151, v151 row_mirror row_mask:0xf bank_mask:0x3 bound_ctrl:1
	v_add_f32_dpp v233, v159, v159 row_mirror row_mask:0xf bank_mask:0xc bound_ctrl:1
	v_add_f32_dpp v234, v152, v152 row_mirror row_mask:0xf bank_mask:0x3 bound_ctrl:1
	v_add_f32_dpp v234, v160, v160 row_mirror row_mask:0xf bank_mask:0xc bound_ctrl:1
	v_add_f32_dpp v235, v153, v153 row_mirror row_mask:0xf bank_mask:0x3 bound_ctrl:1
	v_add_f32_dpp v235, v161, v161 row_mirror row_mask:0xf bank_mask:0xc bound_ctrl:1
	v_add_f32_dpp v236, v154, v154 row_mirror row_mask:0xf bank_mask:0x3 bound_ctrl:1
	v_add_f32_dpp v236, v162, v162 row_mirror row_mask:0xf bank_mask:0xc bound_ctrl:1
	v_add_f32_dpp v237, v155, v155 row_mirror row_mask:0xf bank_mask:0x3 bound_ctrl:1
	v_add_f32_dpp v237, v163, v163 row_mirror row_mask:0xf bank_mask:0xc bound_ctrl:1
	v_add_f32_dpp v238, v230, v230 row_half_mirror row_mask:0xf bank_mask:0x5 bound_ctrl:1
	v_add_f32_dpp v238, v234, v234 row_half_mirror row_mask:0xf bank_mask:0xa bound_ctrl:1
	v_add_f32_dpp v239, v231, v231 row_half_mirror row_mask:0xf bank_mask:0x5 bound_ctrl:1
	v_add_f32_dpp v239, v235, v235 row_half_mirror row_mask:0xf bank_mask:0xa bound_ctrl:1
	v_add_f32_dpp v240, v232, v232 row_half_mirror row_mask:0xf bank_mask:0x5 bound_ctrl:1
	v_add_f32_dpp v240, v236, v236 row_half_mirror row_mask:0xf bank_mask:0xa bound_ctrl:1
	v_add_f32_dpp v241, v233, v233 row_half_mirror row_mask:0xf bank_mask:0x5 bound_ctrl:1
	v_add_f32_dpp v241, v237, v237 row_half_mirror row_mask:0xf bank_mask:0xa bound_ctrl:1
	s_mov_b32 vcc_lo, 0xcccccccc
	s_mov_b32 vcc_hi, 0xcccccccc
	v_cndmask_b32 v244, v240, v238, vcc
	v_cndmask_b32 v245, v241, v239, vcc
	v_cndmask_b32 v242, v238, v240, vcc
	v_cndmask_b32 v243, v239, v241, vcc
	v_add_f32_dpp v242, v244, v242 quad_perm:[2,3,0,1] row_mask:0xf bank_mask:0xf bound_ctrl:1
	v_add_f32_dpp v243, v245, v243 quad_perm:[2,3,0,1] row_mask:0xf bank_mask:0xf bound_ctrl:1
	s_mov_b32 vcc_lo, 0xaaaaaaaa
	s_mov_b32 vcc_hi, 0xaaaaaaaa
	v_cndmask_b32 v244, v243, v242, vcc
	v_cndmask_b32 v245, v242, v243, vcc
	s_nop 0
	v_add_f32_dpp v18, v244, v245 quad_perm:[1,0,3,2] row_mask:0xf bank_mask:0xf bound_ctrl:1
	ds_read_b128 v[230:233], v5 offset:29184
	ds_read_b128 v[234:237], v5 offset:29440
	ds_read_b128 v[238:241], v5 offset:29696
	ds_read_b128 v[242:245], v5 offset:29952
	ds_read_b128 v[246:249], v5 offset:30208
	ds_read_b32 v250, v9 offset:29184
	v_add_f32_dpp v146, v146, v146 quad_perm:[1,0,3,2] row_mask:0xf bank_mask:0xf bound_ctrl:1
	v_pk_mul_f32 v[180:181], v[138:139], v[180:181]
	v_pk_fma_f32 v[180:181], v[140:141], v[182:183], v[180:181]
	v_add_f32_dpp v146, v146, v146 quad_perm:[2,3,0,1] row_mask:0xf bank_mask:0xf bound_ctrl:1
	v_add_f32 v148, v180, v181
	v_pk_mul_f32 v[198:199], v[198:199], v[206:207] op_sel_hi:[1,0]
	v_add_f32_dpp v146, v146, v146 row_half_mirror row_mask:0xf bank_mask:0xf bound_ctrl:1
	v_pk_mul_f32 v[200:201], v[200:201], v[206:207] op_sel_hi:[1,0]
	s_waitcnt lgkmcnt(6)
	v_add_f32_dpp v146, v146, v146 row_mirror row_mask:0xf bank_mask:0xf bound_ctrl:1
	v_pk_fma_f32 v[198:199], v[146:147], v[190:191], v[198:199] op_sel_hi:[0,1,1] neg_lo:[1,0,0] neg_hi:[1,0,0]
	v_pk_fma_f32 v[200:201], v[146:147], v[192:193], v[200:201] op_sel_hi:[0,1,1] neg_lo:[1,0,0] neg_hi:[1,0,0]
	v_pk_fma_f32 v[138:139], v[138:139], v[194:195], v[198:199]
	v_pk_fma_f32 v[140:141], v[140:141], v[196:197], v[200:201]
	v_pk_mul_f32 v[144:145], v[138:139], v[208:209]
	v_pk_fma_f32 v[144:145], v[140:141], v[210:211], v[144:145]
	v_add_f32 v146, v144, v145
	ds_read_b128 v[164:167], v5 offset:30720
	ds_read_b128 v[168:171], v5 offset:30976
	ds_read_b128 v[172:175], v5 offset:31232
	ds_read_b128 v[176:179], v5 offset:31488
	ds_read_b128 v[180:183], v5 offset:31744
	ds_read_b32 v184, v9 offset:30720
	v_add_f32_dpp v146, v146, v146 quad_perm:[1,0,3,2] row_mask:0xf bank_mask:0xf bound_ctrl:1
	v_pk_mul_f32 v[202:203], v[138:139], v[202:203]
	v_pk_fma_f32 v[202:203], v[140:141], v[204:205], v[202:203]
	v_add_f32_dpp v146, v146, v146 quad_perm:[2,3,0,1] row_mask:0xf bank_mask:0xf bound_ctrl:1
	v_add_f32 v149, v202, v203
	v_pk_mul_f32 v[220:221], v[220:221], v[228:229] op_sel_hi:[1,0]
	v_add_f32_dpp v146, v146, v146 row_half_mirror row_mask:0xf bank_mask:0xf bound_ctrl:1
	v_pk_mul_f32 v[222:223], v[222:223], v[228:229] op_sel_hi:[1,0]
	s_waitcnt lgkmcnt(6)
	v_add_f32_dpp v146, v146, v146 row_mirror row_mask:0xf bank_mask:0xf bound_ctrl:1
	v_pk_fma_f32 v[220:221], v[146:147], v[212:213], v[220:221] op_sel_hi:[0,1,1] neg_lo:[1,0,0] neg_hi:[1,0,0]
	v_pk_fma_f32 v[222:223], v[146:147], v[214:215], v[222:223] op_sel_hi:[0,1,1] neg_lo:[1,0,0] neg_hi:[1,0,0]
	v_pk_fma_f32 v[138:139], v[138:139], v[216:217], v[220:221]
	v_pk_fma_f32 v[140:141], v[140:141], v[218:219], v[222:223]
	v_pk_mul_f32 v[144:145], v[138:139], v[230:231]
	v_pk_fma_f32 v[144:145], v[140:141], v[232:233], v[144:145]
	v_add_f32 v146, v144, v145
	ds_read_b128 v[186:189], v5 offset:32256
	ds_read_b128 v[190:193], v5 offset:32512
	ds_read_b128 v[194:197], v5 offset:32768
	ds_read_b128 v[198:201], v5 offset:33024
	ds_read_b128 v[202:205], v5 offset:33280
	ds_read_b32 v206, v9 offset:32256
	v_add_f32_dpp v146, v146, v146 quad_perm:[1,0,3,2] row_mask:0xf bank_mask:0xf bound_ctrl:1
	v_pk_mul_f32 v[224:225], v[138:139], v[224:225]
	v_pk_fma_f32 v[224:225], v[140:141], v[226:227], v[224:225]
	v_add_f32_dpp v146, v146, v146 quad_perm:[2,3,0,1] row_mask:0xf bank_mask:0xf bound_ctrl:1
	v_add_f32 v150, v224, v225
	v_pk_mul_f32 v[242:243], v[242:243], v[250:251] op_sel_hi:[1,0]
	v_add_f32_dpp v146, v146, v146 row_half_mirror row_mask:0xf bank_mask:0xf bound_ctrl:1
	v_pk_mul_f32 v[244:245], v[244:245], v[250:251] op_sel_hi:[1,0]
	s_waitcnt lgkmcnt(6)
	v_add_f32_dpp v146, v146, v146 row_mirror row_mask:0xf bank_mask:0xf bound_ctrl:1
	v_pk_fma_f32 v[242:243], v[146:147], v[234:235], v[242:243] op_sel_hi:[0,1,1] neg_lo:[1,0,0] neg_hi:[1,0,0]
	v_pk_fma_f32 v[244:245], v[146:147], v[236:237], v[244:245] op_sel_hi:[0,1,1] neg_lo:[1,0,0] neg_hi:[1,0,0]
	v_pk_fma_f32 v[138:139], v[138:139], v[238:239], v[242:243]
	v_pk_fma_f32 v[140:141], v[140:141], v[240:241], v[244:245]
	v_pk_mul_f32 v[144:145], v[138:139], v[164:165]
	v_pk_fma_f32 v[144:145], v[140:141], v[166:167], v[144:145]
	v_add_f32 v146, v144, v145
	ds_read_b128 v[208:211], v5 offset:33792
	ds_read_b128 v[212:215], v5 offset:34048
	ds_read_b128 v[216:219], v5 offset:34304
	ds_read_b128 v[220:223], v5 offset:34560
	ds_read_b128 v[224:227], v5 offset:34816
	ds_read_b32 v228, v9 offset:33792
	v_add_f32_dpp v146, v146, v146 quad_perm:[1,0,3,2] row_mask:0xf bank_mask:0xf bound_ctrl:1
	v_pk_mul_f32 v[246:247], v[138:139], v[246:247]
	v_pk_fma_f32 v[246:247], v[140:141], v[248:249], v[246:247]
	v_add_f32_dpp v146, v146, v146 quad_perm:[2,3,0,1] row_mask:0xf bank_mask:0xf bound_ctrl:1
	v_add_f32 v151, v246, v247
	v_pk_mul_f32 v[176:177], v[176:177], v[184:185] op_sel_hi:[1,0]
	v_add_f32_dpp v146, v146, v146 row_half_mirror row_mask:0xf bank_mask:0xf bound_ctrl:1
	v_pk_mul_f32 v[178:179], v[178:179], v[184:185] op_sel_hi:[1,0]
	s_waitcnt lgkmcnt(6)
	v_add_f32_dpp v146, v146, v146 row_mirror row_mask:0xf bank_mask:0xf bound_ctrl:1
	v_pk_fma_f32 v[176:177], v[146:147], v[168:169], v[176:177] op_sel_hi:[0,1,1] neg_lo:[1,0,0] neg_hi:[1,0,0]
	v_pk_fma_f32 v[178:179], v[146:147], v[170:171], v[178:179] op_sel_hi:[0,1,1] neg_lo:[1,0,0] neg_hi:[1,0,0]
	v_pk_fma_f32 v[138:139], v[138:139], v[172:173], v[176:177]
	v_pk_fma_f32 v[140:141], v[140:141], v[174:175], v[178:179]
	v_pk_mul_f32 v[144:145], v[138:139], v[186:187]
	v_pk_fma_f32 v[144:145], v[140:141], v[188:189], v[144:145]
	v_add_f32 v146, v144, v145
	ds_read_b128 v[230:233], v5 offset:35328
	ds_read_b128 v[234:237], v5 offset:35584
	ds_read_b128 v[238:241], v5 offset:35840
	ds_read_b128 v[242:245], v5 offset:36096
	ds_read_b128 v[246:249], v5 offset:36352
	ds_read_b32 v250, v9 offset:35328
	v_add_f32_dpp v146, v146, v146 quad_perm:[1,0,3,2] row_mask:0xf bank_mask:0xf bound_ctrl:1
	v_pk_mul_f32 v[180:181], v[138:139], v[180:181]
	v_pk_fma_f32 v[180:181], v[140:141], v[182:183], v[180:181]
	v_add_f32_dpp v146, v146, v146 quad_perm:[2,3,0,1] row_mask:0xf bank_mask:0xf bound_ctrl:1
	v_add_f32 v152, v180, v181
	v_pk_mul_f32 v[198:199], v[198:199], v[206:207] op_sel_hi:[1,0]
	v_add_f32_dpp v146, v146, v146 row_half_mirror row_mask:0xf bank_mask:0xf bound_ctrl:1
	v_pk_mul_f32 v[200:201], v[200:201], v[206:207] op_sel_hi:[1,0]
	s_waitcnt lgkmcnt(6)
	v_add_f32_dpp v146, v146, v146 row_mirror row_mask:0xf bank_mask:0xf bound_ctrl:1
	v_pk_fma_f32 v[198:199], v[146:147], v[190:191], v[198:199] op_sel_hi:[0,1,1] neg_lo:[1,0,0] neg_hi:[1,0,0]
	v_pk_fma_f32 v[200:201], v[146:147], v[192:193], v[200:201] op_sel_hi:[0,1,1] neg_lo:[1,0,0] neg_hi:[1,0,0]
	v_pk_fma_f32 v[138:139], v[138:139], v[194:195], v[198:199]
	v_pk_fma_f32 v[140:141], v[140:141], v[196:197], v[200:201]
	v_pk_mul_f32 v[144:145], v[138:139], v[208:209]
	v_pk_fma_f32 v[144:145], v[140:141], v[210:211], v[144:145]
	v_add_f32 v146, v144, v145
	ds_read_b128 v[164:167], v5 offset:36864
	ds_read_b128 v[168:171], v5 offset:37120
	ds_read_b128 v[172:175], v5 offset:37376
	ds_read_b128 v[176:179], v5 offset:37632
	ds_read_b128 v[180:183], v5 offset:37888
	ds_read_b32 v184, v9 offset:36864
	v_add_f32_dpp v146, v146, v146 quad_perm:[1,0,3,2] row_mask:0xf bank_mask:0xf bound_ctrl:1
	v_pk_mul_f32 v[202:203], v[138:139], v[202:203]
	v_pk_fma_f32 v[202:203], v[140:141], v[204:205], v[202:203]
	v_add_f32_dpp v146, v146, v146 quad_perm:[2,3,0,1] row_mask:0xf bank_mask:0xf bound_ctrl:1
	v_add_f32 v153, v202, v203
	v_pk_mul_f32 v[220:221], v[220:221], v[228:229] op_sel_hi:[1,0]
	v_add_f32_dpp v146, v146, v146 row_half_mirror row_mask:0xf bank_mask:0xf bound_ctrl:1
	v_pk_mul_f32 v[222:223], v[222:223], v[228:229] op_sel_hi:[1,0]
	s_waitcnt lgkmcnt(6)
	v_add_f32_dpp v146, v146, v146 row_mirror row_mask:0xf bank_mask:0xf bound_ctrl:1
	v_pk_fma_f32 v[220:221], v[146:147], v[212:213], v[220:221] op_sel_hi:[0,1,1] neg_lo:[1,0,0] neg_hi:[1,0,0]
	v_pk_fma_f32 v[222:223], v[146:147], v[214:215], v[222:223] op_sel_hi:[0,1,1] neg_lo:[1,0,0] neg_hi:[1,0,0]
	v_pk_fma_f32 v[138:139], v[138:139], v[216:217], v[220:221]
	v_pk_fma_f32 v[140:141], v[140:141], v[218:219], v[222:223]
	v_pk_mul_f32 v[144:145], v[138:139], v[230:231]
	v_pk_fma_f32 v[144:145], v[140:141], v[232:233], v[144:145]
	v_add_f32 v146, v144, v145
	ds_read_b128 v[186:189], v5 offset:38400
	ds_read_b128 v[190:193], v5 offset:38656
	ds_read_b128 v[194:197], v5 offset:38912
	ds_read_b128 v[198:201], v5 offset:39168
	ds_read_b128 v[202:205], v5 offset:39424
	ds_read_b32 v206, v9 offset:38400
	v_add_f32_dpp v146, v146, v146 quad_perm:[1,0,3,2] row_mask:0xf bank_mask:0xf bound_ctrl:1
	v_pk_mul_f32 v[224:225], v[138:139], v[224:225]
	v_pk_fma_f32 v[224:225], v[140:141], v[226:227], v[224:225]
	v_add_f32_dpp v146, v146, v146 quad_perm:[2,3,0,1] row_mask:0xf bank_mask:0xf bound_ctrl:1
	v_add_f32 v154, v224, v225
	v_pk_mul_f32 v[242:243], v[242:243], v[250:251] op_sel_hi:[1,0]
	v_add_f32_dpp v146, v146, v146 row_half_mirror row_mask:0xf bank_mask:0xf bound_ctrl:1
	v_pk_mul_f32 v[244:245], v[244:245], v[250:251] op_sel_hi:[1,0]
	s_waitcnt lgkmcnt(6)
	v_add_f32_dpp v146, v146, v146 row_mirror row_mask:0xf bank_mask:0xf bound_ctrl:1
	v_pk_fma_f32 v[242:243], v[146:147], v[234:235], v[242:243] op_sel_hi:[0,1,1] neg_lo:[1,0,0] neg_hi:[1,0,0]
	v_pk_fma_f32 v[244:245], v[146:147], v[236:237], v[244:245] op_sel_hi:[0,1,1] neg_lo:[1,0,0] neg_hi:[1,0,0]
	v_pk_fma_f32 v[138:139], v[138:139], v[238:239], v[242:243]
	v_pk_fma_f32 v[140:141], v[140:141], v[240:241], v[244:245]
	v_pk_mul_f32 v[144:145], v[138:139], v[164:165]
	v_pk_fma_f32 v[144:145], v[140:141], v[166:167], v[144:145]
	v_add_f32 v146, v144, v145
	ds_read_b128 v[208:211], v5 offset:39936
	ds_read_b128 v[212:215], v5 offset:40192
	ds_read_b128 v[216:219], v5 offset:40448
	ds_read_b128 v[220:223], v5 offset:40704
	ds_read_b128 v[224:227], v5 offset:40960
	ds_read_b32 v228, v9 offset:39936
	v_add_f32_dpp v146, v146, v146 quad_perm:[1,0,3,2] row_mask:0xf bank_mask:0xf bound_ctrl:1
	v_pk_mul_f32 v[246:247], v[138:139], v[246:247]
	v_pk_fma_f32 v[246:247], v[140:141], v[248:249], v[246:247]
	v_add_f32_dpp v146, v146, v146 quad_perm:[2,3,0,1] row_mask:0xf bank_mask:0xf bound_ctrl:1
	v_add_f32 v155, v246, v247
	v_pk_mul_f32 v[176:177], v[176:177], v[184:185] op_sel_hi:[1,0]
	v_add_f32_dpp v146, v146, v146 row_half_mirror row_mask:0xf bank_mask:0xf bound_ctrl:1
	v_pk_mul_f32 v[178:179], v[178:179], v[184:185] op_sel_hi:[1,0]
	s_waitcnt lgkmcnt(6)
	v_add_f32_dpp v146, v146, v146 row_mirror row_mask:0xf bank_mask:0xf bound_ctrl:1
	v_pk_fma_f32 v[176:177], v[146:147], v[168:169], v[176:177] op_sel_hi:[0,1,1] neg_lo:[1,0,0] neg_hi:[1,0,0]
	v_pk_fma_f32 v[178:179], v[146:147], v[170:171], v[178:179] op_sel_hi:[0,1,1] neg_lo:[1,0,0] neg_hi:[1,0,0]
	v_pk_fma_f32 v[138:139], v[138:139], v[172:173], v[176:177]
	v_pk_fma_f32 v[140:141], v[140:141], v[174:175], v[178:179]
	v_pk_mul_f32 v[144:145], v[138:139], v[186:187]
	v_pk_fma_f32 v[144:145], v[140:141], v[188:189], v[144:145]
	v_add_f32 v146, v144, v145
	ds_read_b128 v[230:233], v5 offset:41472
	ds_read_b128 v[234:237], v5 offset:41728
	ds_read_b128 v[238:241], v5 offset:41984
	ds_read_b128 v[242:245], v5 offset:42240
	ds_read_b128 v[246:249], v5 offset:42496
	ds_read_b32 v250, v9 offset:41472
	v_add_f32_dpp v146, v146, v146 quad_perm:[1,0,3,2] row_mask:0xf bank_mask:0xf bound_ctrl:1
	v_pk_mul_f32 v[180:181], v[138:139], v[180:181]
	v_pk_fma_f32 v[180:181], v[140:141], v[182:183], v[180:181]
	v_add_f32_dpp v146, v146, v146 quad_perm:[2,3,0,1] row_mask:0xf bank_mask:0xf bound_ctrl:1
	v_add_f32 v156, v180, v181
	v_pk_mul_f32 v[198:199], v[198:199], v[206:207] op_sel_hi:[1,0]
	v_add_f32_dpp v146, v146, v146 row_half_mirror row_mask:0xf bank_mask:0xf bound_ctrl:1
	v_pk_mul_f32 v[200:201], v[200:201], v[206:207] op_sel_hi:[1,0]
	s_waitcnt lgkmcnt(6)
	v_add_f32_dpp v146, v146, v146 row_mirror row_mask:0xf bank_mask:0xf bound_ctrl:1
	v_pk_fma_f32 v[198:199], v[146:147], v[190:191], v[198:199] op_sel_hi:[0,1,1] neg_lo:[1,0,0] neg_hi:[1,0,0]
	v_pk_fma_f32 v[200:201], v[146:147], v[192:193], v[200:201] op_sel_hi:[0,1,1] neg_lo:[1,0,0] neg_hi:[1,0,0]
	v_pk_fma_f32 v[138:139], v[138:139], v[194:195], v[198:199]
	v_pk_fma_f32 v[140:141], v[140:141], v[196:197], v[200:201]
	v_pk_mul_f32 v[144:145], v[138:139], v[208:209]
	v_pk_fma_f32 v[144:145], v[140:141], v[210:211], v[144:145]
	v_add_f32 v146, v144, v145
	ds_read_b128 v[164:167], v5 offset:43008
	ds_read_b128 v[168:171], v5 offset:43264
	ds_read_b128 v[172:175], v5 offset:43520
	ds_read_b128 v[176:179], v5 offset:43776
	ds_read_b128 v[180:183], v5 offset:44032
	ds_read_b32 v184, v9 offset:43008
	v_add_f32_dpp v146, v146, v146 quad_perm:[1,0,3,2] row_mask:0xf bank_mask:0xf bound_ctrl:1
	v_pk_mul_f32 v[202:203], v[138:139], v[202:203]
	v_pk_fma_f32 v[202:203], v[140:141], v[204:205], v[202:203]
	v_add_f32_dpp v146, v146, v146 quad_perm:[2,3,0,1] row_mask:0xf bank_mask:0xf bound_ctrl:1
	v_add_f32 v157, v202, v203
	v_pk_mul_f32 v[220:221], v[220:221], v[228:229] op_sel_hi:[1,0]
	v_add_f32_dpp v146, v146, v146 row_half_mirror row_mask:0xf bank_mask:0xf bound_ctrl:1
	v_pk_mul_f32 v[222:223], v[222:223], v[228:229] op_sel_hi:[1,0]
	s_waitcnt lgkmcnt(6)
	v_add_f32_dpp v146, v146, v146 row_mirror row_mask:0xf bank_mask:0xf bound_ctrl:1
	v_pk_fma_f32 v[220:221], v[146:147], v[212:213], v[220:221] op_sel_hi:[0,1,1] neg_lo:[1,0,0] neg_hi:[1,0,0]
	v_pk_fma_f32 v[222:223], v[146:147], v[214:215], v[222:223] op_sel_hi:[0,1,1] neg_lo:[1,0,0] neg_hi:[1,0,0]
	v_pk_fma_f32 v[138:139], v[138:139], v[216:217], v[220:221]
	v_pk_fma_f32 v[140:141], v[140:141], v[218:219], v[222:223]
	v_pk_mul_f32 v[144:145], v[138:139], v[230:231]
	v_pk_fma_f32 v[144:145], v[140:141], v[232:233], v[144:145]
	v_add_f32 v146, v144, v145
	ds_read_b128 v[186:189], v5 offset:44544
	ds_read_b128 v[190:193], v5 offset:44800
	ds_read_b128 v[194:197], v5 offset:45056
	ds_read_b128 v[198:201], v5 offset:45312
	ds_read_b128 v[202:205], v5 offset:45568
	ds_read_b32 v206, v9 offset:44544
	v_add_f32_dpp v146, v146, v146 quad_perm:[1,0,3,2] row_mask:0xf bank_mask:0xf bound_ctrl:1
	v_pk_mul_f32 v[224:225], v[138:139], v[224:225]
	v_pk_fma_f32 v[224:225], v[140:141], v[226:227], v[224:225]
	v_add_f32_dpp v146, v146, v146 quad_perm:[2,3,0,1] row_mask:0xf bank_mask:0xf bound_ctrl:1
	v_add_f32 v158, v224, v225
	v_pk_mul_f32 v[242:243], v[242:243], v[250:251] op_sel_hi:[1,0]
	v_add_f32_dpp v146, v146, v146 row_half_mirror row_mask:0xf bank_mask:0xf bound_ctrl:1
	v_pk_mul_f32 v[244:245], v[244:245], v[250:251] op_sel_hi:[1,0]
	s_waitcnt lgkmcnt(6)
	v_add_f32_dpp v146, v146, v146 row_mirror row_mask:0xf bank_mask:0xf bound_ctrl:1
	v_pk_fma_f32 v[242:243], v[146:147], v[234:235], v[242:243] op_sel_hi:[0,1,1] neg_lo:[1,0,0] neg_hi:[1,0,0]
	v_pk_fma_f32 v[244:245], v[146:147], v[236:237], v[244:245] op_sel_hi:[0,1,1] neg_lo:[1,0,0] neg_hi:[1,0,0]
	v_pk_fma_f32 v[138:139], v[138:139], v[238:239], v[242:243]
	v_pk_fma_f32 v[140:141], v[140:141], v[240:241], v[244:245]
	v_pk_mul_f32 v[144:145], v[138:139], v[164:165]
	v_pk_fma_f32 v[144:145], v[140:141], v[166:167], v[144:145]
	v_add_f32 v146, v144, v145
	ds_read_b128 v[208:211], v5 offset:46080
	ds_read_b128 v[212:215], v5 offset:46336
	ds_read_b128 v[216:219], v5 offset:46592
	ds_read_b128 v[220:223], v5 offset:46848
	ds_read_b128 v[224:227], v5 offset:47104
	ds_read_b32 v228, v9 offset:46080
	v_add_f32_dpp v146, v146, v146 quad_perm:[1,0,3,2] row_mask:0xf bank_mask:0xf bound_ctrl:1
	v_pk_mul_f32 v[246:247], v[138:139], v[246:247]
	v_pk_fma_f32 v[246:247], v[140:141], v[248:249], v[246:247]
	v_add_f32_dpp v146, v146, v146 quad_perm:[2,3,0,1] row_mask:0xf bank_mask:0xf bound_ctrl:1
	v_add_f32 v159, v246, v247
	v_pk_mul_f32 v[176:177], v[176:177], v[184:185] op_sel_hi:[1,0]
	v_add_f32_dpp v146, v146, v146 row_half_mirror row_mask:0xf bank_mask:0xf bound_ctrl:1
	v_pk_mul_f32 v[178:179], v[178:179], v[184:185] op_sel_hi:[1,0]
	s_waitcnt lgkmcnt(6)
	v_add_f32_dpp v146, v146, v146 row_mirror row_mask:0xf bank_mask:0xf bound_ctrl:1
	v_pk_fma_f32 v[176:177], v[146:147], v[168:169], v[176:177] op_sel_hi:[0,1,1] neg_lo:[1,0,0] neg_hi:[1,0,0]
	v_pk_fma_f32 v[178:179], v[146:147], v[170:171], v[178:179] op_sel_hi:[0,1,1] neg_lo:[1,0,0] neg_hi:[1,0,0]
	v_pk_fma_f32 v[138:139], v[138:139], v[172:173], v[176:177]
	v_pk_fma_f32 v[140:141], v[140:141], v[174:175], v[178:179]
	v_pk_mul_f32 v[144:145], v[138:139], v[186:187]
	v_pk_fma_f32 v[144:145], v[140:141], v[188:189], v[144:145]
	v_add_f32 v146, v144, v145
	ds_read_b128 v[230:233], v5 offset:47616
	ds_read_b128 v[234:237], v5 offset:47872
	ds_read_b128 v[238:241], v5 offset:48128
	ds_read_b128 v[242:245], v5 offset:48384
	ds_read_b128 v[246:249], v5 offset:48640
	ds_read_b32 v250, v9 offset:47616
	v_add_f32_dpp v146, v146, v146 quad_perm:[1,0,3,2] row_mask:0xf bank_mask:0xf bound_ctrl:1
	v_pk_mul_f32 v[180:181], v[138:139], v[180:181]
	v_pk_fma_f32 v[180:181], v[140:141], v[182:183], v[180:181]
	v_add_f32_dpp v146, v146, v146 quad_perm:[2,3,0,1] row_mask:0xf bank_mask:0xf bound_ctrl:1
	v_add_f32 v160, v180, v181
	v_pk_mul_f32 v[198:199], v[198:199], v[206:207] op_sel_hi:[1,0]
	v_add_f32_dpp v146, v146, v146 row_half_mirror row_mask:0xf bank_mask:0xf bound_ctrl:1
	v_pk_mul_f32 v[200:201], v[200:201], v[206:207] op_sel_hi:[1,0]
	s_waitcnt lgkmcnt(6)
	v_add_f32_dpp v146, v146, v146 row_mirror row_mask:0xf bank_mask:0xf bound_ctrl:1
	v_pk_fma_f32 v[198:199], v[146:147], v[190:191], v[198:199] op_sel_hi:[0,1,1] neg_lo:[1,0,0] neg_hi:[1,0,0]
	v_pk_fma_f32 v[200:201], v[146:147], v[192:193], v[200:201] op_sel_hi:[0,1,1] neg_lo:[1,0,0] neg_hi:[1,0,0]
	v_pk_fma_f32 v[138:139], v[138:139], v[194:195], v[198:199]
	v_pk_fma_f32 v[140:141], v[140:141], v[196:197], v[200:201]
	v_pk_mul_f32 v[144:145], v[138:139], v[208:209]
	v_pk_fma_f32 v[144:145], v[140:141], v[210:211], v[144:145]
	v_add_f32 v146, v144, v145
	s_nop 1
	v_add_f32_dpp v146, v146, v146 quad_perm:[1,0,3,2] row_mask:0xf bank_mask:0xf bound_ctrl:1
	v_pk_mul_f32 v[202:203], v[138:139], v[202:203]
	v_pk_fma_f32 v[202:203], v[140:141], v[204:205], v[202:203]
	v_add_f32_dpp v146, v146, v146 quad_perm:[2,3,0,1] row_mask:0xf bank_mask:0xf bound_ctrl:1
	v_add_f32 v161, v202, v203
	v_pk_mul_f32 v[220:221], v[220:221], v[228:229] op_sel_hi:[1,0]
	v_add_f32_dpp v146, v146, v146 row_half_mirror row_mask:0xf bank_mask:0xf bound_ctrl:1
	v_pk_mul_f32 v[222:223], v[222:223], v[228:229] op_sel_hi:[1,0]
	s_waitcnt lgkmcnt(0)
	v_add_f32_dpp v146, v146, v146 row_mirror row_mask:0xf bank_mask:0xf bound_ctrl:1
	v_pk_fma_f32 v[220:221], v[146:147], v[212:213], v[220:221] op_sel_hi:[0,1,1] neg_lo:[1,0,0] neg_hi:[1,0,0]
	v_pk_fma_f32 v[222:223], v[146:147], v[214:215], v[222:223] op_sel_hi:[0,1,1] neg_lo:[1,0,0] neg_hi:[1,0,0]
	v_pk_fma_f32 v[138:139], v[138:139], v[216:217], v[220:221]
	v_pk_fma_f32 v[140:141], v[140:141], v[218:219], v[222:223]
	v_pk_mul_f32 v[144:145], v[138:139], v[230:231]
	v_pk_fma_f32 v[144:145], v[140:141], v[232:233], v[144:145]
	v_add_f32 v146, v144, v145
	s_nop 1
	v_add_f32_dpp v146, v146, v146 quad_perm:[1,0,3,2] row_mask:0xf bank_mask:0xf bound_ctrl:1
	v_pk_mul_f32 v[224:225], v[138:139], v[224:225]
	v_pk_fma_f32 v[224:225], v[140:141], v[226:227], v[224:225]
	v_add_f32_dpp v146, v146, v146 quad_perm:[2,3,0,1] row_mask:0xf bank_mask:0xf bound_ctrl:1
	v_add_f32 v162, v224, v225
	v_pk_mul_f32 v[242:243], v[242:243], v[250:251] op_sel_hi:[1,0]
	v_add_f32_dpp v146, v146, v146 row_half_mirror row_mask:0xf bank_mask:0xf bound_ctrl:1
	v_pk_mul_f32 v[244:245], v[244:245], v[250:251] op_sel_hi:[1,0]
	s_nop 0
	v_add_f32_dpp v146, v146, v146 row_mirror row_mask:0xf bank_mask:0xf bound_ctrl:1
	v_pk_fma_f32 v[242:243], v[146:147], v[234:235], v[242:243] op_sel_hi:[0,1,1] neg_lo:[1,0,0] neg_hi:[1,0,0]
	v_pk_fma_f32 v[244:245], v[146:147], v[236:237], v[244:245] op_sel_hi:[0,1,1] neg_lo:[1,0,0] neg_hi:[1,0,0]
	v_pk_fma_f32 v[138:139], v[138:139], v[238:239], v[242:243]
	v_pk_fma_f32 v[140:141], v[140:141], v[240:241], v[244:245]
	v_pk_mul_f32 v[246:247], v[138:139], v[246:247]
	v_pk_fma_f32 v[246:247], v[140:141], v[248:249], v[246:247]
	v_add_f32 v163, v246, v247
	s_nop 0
	v_add_f32_dpp v230, v148, v148 row_mirror row_mask:0xf bank_mask:0x3 bound_ctrl:1
	v_add_f32_dpp v230, v156, v156 row_mirror row_mask:0xf bank_mask:0xc bound_ctrl:1
	v_add_f32_dpp v231, v149, v149 row_mirror row_mask:0xf bank_mask:0x3 bound_ctrl:1
	v_add_f32_dpp v231, v157, v157 row_mirror row_mask:0xf bank_mask:0xc bound_ctrl:1
	v_add_f32_dpp v232, v150, v150 row_mirror row_mask:0xf bank_mask:0x3 bound_ctrl:1
	v_add_f32_dpp v232, v158, v158 row_mirror row_mask:0xf bank_mask:0xc bound_ctrl:1
	v_add_f32_dpp v233, v151, v151 row_mirror row_mask:0xf bank_mask:0x3 bound_ctrl:1
	v_add_f32_dpp v233, v159, v159 row_mirror row_mask:0xf bank_mask:0xc bound_ctrl:1
	v_add_f32_dpp v234, v152, v152 row_mirror row_mask:0xf bank_mask:0x3 bound_ctrl:1
	v_add_f32_dpp v234, v160, v160 row_mirror row_mask:0xf bank_mask:0xc bound_ctrl:1
	v_add_f32_dpp v235, v153, v153 row_mirror row_mask:0xf bank_mask:0x3 bound_ctrl:1
	v_add_f32_dpp v235, v161, v161 row_mirror row_mask:0xf bank_mask:0xc bound_ctrl:1
	v_add_f32_dpp v236, v154, v154 row_mirror row_mask:0xf bank_mask:0x3 bound_ctrl:1
	v_add_f32_dpp v236, v162, v162 row_mirror row_mask:0xf bank_mask:0xc bound_ctrl:1
	v_add_f32_dpp v237, v155, v155 row_mirror row_mask:0xf bank_mask:0x3 bound_ctrl:1
	v_add_f32_dpp v237, v163, v163 row_mirror row_mask:0xf bank_mask:0xc bound_ctrl:1
	v_add_f32_dpp v238, v230, v230 row_half_mirror row_mask:0xf bank_mask:0x5 bound_ctrl:1
	v_add_f32_dpp v238, v234, v234 row_half_mirror row_mask:0xf bank_mask:0xa bound_ctrl:1
	v_add_f32_dpp v239, v231, v231 row_half_mirror row_mask:0xf bank_mask:0x5 bound_ctrl:1
	v_add_f32_dpp v239, v235, v235 row_half_mirror row_mask:0xf bank_mask:0xa bound_ctrl:1
	v_add_f32_dpp v240, v232, v232 row_half_mirror row_mask:0xf bank_mask:0x5 bound_ctrl:1
	v_add_f32_dpp v240, v236, v236 row_half_mirror row_mask:0xf bank_mask:0xa bound_ctrl:1
	v_add_f32_dpp v241, v233, v233 row_half_mirror row_mask:0xf bank_mask:0x5 bound_ctrl:1
	v_add_f32_dpp v241, v237, v237 row_half_mirror row_mask:0xf bank_mask:0xa bound_ctrl:1
	s_mov_b32 vcc_lo, 0xcccccccc
	s_mov_b32 vcc_hi, 0xcccccccc
	v_cndmask_b32 v244, v240, v238, vcc
	v_cndmask_b32 v245, v241, v239, vcc
	v_cndmask_b32 v242, v238, v240, vcc
	v_cndmask_b32 v243, v239, v241, vcc
	v_add_f32_dpp v242, v244, v242 quad_perm:[2,3,0,1] row_mask:0xf bank_mask:0xf bound_ctrl:1
	v_add_f32_dpp v243, v245, v243 quad_perm:[2,3,0,1] row_mask:0xf bank_mask:0xf bound_ctrl:1
	s_mov_b32 vcc_lo, 0xaaaaaaaa
	s_mov_b32 vcc_hi, 0xaaaaaaaa
	v_cndmask_b32 v244, v243, v242, vcc
	v_cndmask_b32 v245, v242, v243, vcc
	s_nop 0
	v_add_f32_dpp v19, v244, v245 quad_perm:[1,0,3,2] row_mask:0xf bank_mask:0xf bound_ctrl:1

; #define SCAN_BAR() asm volatile("s_barrier" ::: "memory")
; __device__ __forceinline__ void scan_unit(const Ctx& C0, const float* scn, int T, int quarter, const float* S0, float* Sout, unsigned char* obase, int mode) {
;     ...
;             const unsigned aq = (unsigned)(size_t)(C.lds + (k & 1) * SLOT_B) + 16u * (unsigned)q, av = (unsigned)(size_t)(C.lds + (k & 1) * SLOT_B) + (320u + (unsigned)irow) * 4u;
;             float osel0, osel1;
;             asm volatile(SCAN_CHUNK_ASM : "+v"(S0x), "+v"(S1x), "+v"(S2x), "+v"(S3x), "=&v"(osel0), "=&v"(osel1) : "v"(aq), "v"(av), "v"(q) : SCAN_CHUNK_CLOBBERS, "memory");
;             if (mode == 0) { *(float*)(obase + (size_t)(k * 32 + q) * UPITCH_B + rl * 4) = osel0; *(float*)(obase + (size_t)(k * 32 + 16 + q) * UPITCH_B + rl * 4) = osel1; }
;             SCAN_BAR();
	v_lshl_add_u64 v[14:15], v[6:7], 0, s[0:1]
	v_add_co_u32_e32 v16, vcc, 0xfc29000, v14
	s_mov_b32 s8, 0xfc7f000
	s_nop 0
	v_addc_co_u32_e32 v17, vcc, 0, v15, vcc
	global_store_dword v[16:17], v18, off offset:768
	v_add_co_u32_e32 v16, vcc, 0xfc54000, v14
	s_add_u32 s0, s0, 0xac000
	s_nop 0
	v_addc_co_u32_e32 v17, vcc, 0, v15, vcc
	global_store_dword v[16:17], v19, off offset:768
	s_barrier
	ds_read_b128 v[164:167], v10 offset:0
	ds_read_b128 v[168:171], v10 offset:256
	ds_read_b128 v[172:175], v10 offset:512
	ds_read_b128 v[176:179], v10 offset:768
	ds_read_b128 v[180:183], v10 offset:1024
	ds_read_b32 v184, v11 offset:0
	ds_read_b128 v[186:189], v10 offset:1536
	ds_read_b128 v[190:193], v10 offset:1792
	ds_read_b128 v[194:197], v10 offset:2048
	ds_read_b128 v[198:201], v10 offset:2304
	ds_read_b128 v[202:205], v10 offset:2560
	ds_read_b32 v206, v11 offset:1536
	s_waitcnt lgkmcnt(0)
	v_pk_mul_f32 v[144:145], v[138:139], v[164:165]
	v_pk_fma_f32 v[144:145], v[140:141], v[166:167], v[144:145]
	v_add_f32 v146, v144, v145
	ds_read_b128 v[208:211], v10 offset:3072
	ds_read_b128 v[212:215], v10 offset:3328
	ds_read_b128 v[216:219], v10 offset:3584
	ds_read_b128 v[220:223], v10 offset:3840
	ds_read_b128 v[224:227], v10 offset:4096
	ds_read_b32 v228, v11 offset:3072
	v_add_f32_dpp v146, v146, v146 quad_perm:[1,0,3,2] row_mask:0xf bank_mask:0xf bound_ctrl:1
	s_nop 0
	s_nop 0
	v_add_f32_dpp v146, v146, v146 quad_perm:[2,3,0,1] row_mask:0xf bank_mask:0xf bound_ctrl:1
	s_nop 0
	v_pk_mul_f32 v[176:177], v[176:177], v[184:185] op_sel_hi:[1,0]
	v_add_f32_dpp v146, v146, v146 row_half_mirror row_mask:0xf bank_mask:0xf bound_ctrl:1
	v_pk_mul_f32 v[178:179], v[178:179], v[184:185] op_sel_hi:[1,0]
	s_waitcnt lgkmcnt(6)
	v_add_f32_dpp v146, v146, v146 row_mirror row_mask:0xf bank_mask:0xf bound_ctrl:1
	v_pk_fma_f32 v[176:177], v[146:147], v[168:169], v[176:177] op_sel_hi:[0,1,1] neg_lo:[1,0,0] neg_hi:[1,0,0]
	v_pk_fma_f32 v[178:179], v[146:147], v[170:171], v[178:179] op_sel_hi:[0,1,1] neg_lo:[1,0,0] neg_hi:[1,0,0]
	v_pk_fma_f32 v[138:139], v[138:139], v[172:173], v[176:177]
	v_pk_fma_f32 v[140:141], v[140:141], v[174:175], v[178:179]
	v_pk_mul_f32 v[144:145], v[138:139], v[186:187]
	v_pk_fma_f32 v[144:145], v[140:141], v[188:189], v[144:145]
	v_add_f32 v146, v144, v145
	ds_read_b128 v[230:233], v10 offset:4608
	ds_read_b128 v[234:237], v10 offset:4864
	ds_read_b128 v[238:241], v10 offset:5120
	ds_read_b128 v[242:245], v10 offset:5376
	ds_read_b128 v[246:249], v10 offset:5632
	ds_read_b32 v250, v11 offset:4608
	v_add_f32_dpp v146, v146, v146 quad_perm:[1,0,3,2] row_mask:0xf bank_mask:0xf bound_ctrl:1
	v_pk_mul_f32 v[180:181], v[138:139], v[180:181]
	v_pk_fma_f32 v[180:181], v[140:141], v[182:183], v[180:181]
	v_add_f32_dpp v146, v146, v146 quad_perm:[2,3,0,1] row_mask:0xf bank_mask:0xf bound_ctrl:1
	v_add_f32 v148, v180, v181
	v_pk_mul_f32 v[198:199], v[198:199], v[206:207] op_sel_hi:[1,0]
	v_add_f32_dpp v146, v146, v146 row_half_mirror row_mask:0xf bank_mask:0xf bound_ctrl:1
	v_pk_mul_f32 v[200:201], v[200:201], v[206:207] op_sel_hi:[1,0]
	s_waitcnt lgkmcnt(6)
	v_add_f32_dpp v146, v146, v146 row_mirror row_mask:0xf bank_mask:0xf bound_ctrl:1
	v_pk_fma_f32 v[198:199], v[146:147], v[190:191], v[198:199] op_sel_hi:[0,1,1] neg_lo:[1,0,0] neg_hi:[1,0,0]
	v_pk_fma_f32 v[200:201], v[146:147], v[192:193], v[200:201] op_sel_hi:[0,1,1] neg_lo:[1,0,0] neg_hi:[1,0,0]
	v_pk_fma_f32 v[138:139], v[138:139], v[194:195], v[198:199]
	v_pk_fma_f32 v[140:141], v[140:141], v[196:197], v[200:201]
	v_pk_mul_f32 v[144:145], v[138:139], v[208:209]
	v_pk_fma_f32 v[144:145], v[140:141], v[210:211], v[144:145]
	v_add_f32 v146, v144, v145
	ds_read_b128 v[164:167], v10 offset:6144
	ds_read_b128 v[168:171], v10 offset:6400
	ds_read_b128 v[172:175], v10 offset:6656
	ds_read_b128 v[176:179], v10 offset:6912
	ds_read_b128 v[180:183], v10 offset:7168
	ds_read_b32 v184, v11 offset:6144
	v_add_f32_dpp v146, v146, v146 quad_perm:[1,0,3,2] row_mask:0xf bank_mask:0xf bound_ctrl:1
	v_pk_mul_f32 v[202:203], v[138:139], v[202:203]
	v_pk_fma_f32 v[202:203], v[140:141], v[204:205], v[202:203]
	v_add_f32_dpp v146, v146, v146 quad_perm:[2,3,0,1] row_mask:0xf bank_mask:0xf bound_ctrl:1
	v_add_f32 v149, v202, v203
	v_pk_mul_f32 v[220:221], v[220:221], v[228:229] op_sel_hi:[1,0]
	v_add_f32_dpp v146, v146, v146 row_half_mirror row_mask:0xf bank_mask:0xf bound_ctrl:1
	v_pk_mul_f32 v[222:223], v[222:223], v[228:229] op_sel_hi:[1,0]
	s_waitcnt lgkmcnt(6)
	v_add_f32_dpp v146, v146, v146 row_mirror row_mask:0xf bank_mask:0xf bound_ctrl:1
	v_pk_fma_f32 v[220:221], v[146:147], v[212:213], v[220:221] op_sel_hi:[0,1,1] neg_lo:[1,0,0] neg_hi:[1,0,0]
	v_pk_fma_f32 v[222:223], v[146:147], v[214:215], v[222:223] op_sel_hi:[0,1,1] neg_lo:[1,0,0] neg_hi:[1,0,0]
	v_pk_fma_f32 v[138:139], v[138:139], v[216:217], v[220:221]
	v_pk_fma_f32 v[140:141], v[140:141], v[218:219], v[222:223]
	v_pk_mul_f32 v[144:145], v[138:139], v[230:231]
	v_pk_fma_f32 v[144:145], v[140:141], v[232:233], v[144:145]
	v_add_f32 v146, v144, v145
	ds_read_b128 v[186:189], v10 offset:7680
	ds_read_b128 v[190:193], v10 offset:7936
	ds_read_b128 v[194:197], v10 offset:8192
	ds_read_b128 v[198:201], v10 offset:8448
	ds_read_b128 v[202:205], v10 offset:8704
	ds_read_b32 v206, v11 offset:7680
	v_add_f32_dpp v146, v146, v146 quad_perm:[1,0,3,2] row_mask:0xf bank_mask:0xf bound_ctrl:1
	v_pk_mul_f32 v[224:225], v[138:139], v[224:225]
	v_pk_fma_f32 v[224:225], v[140:141], v[226:227], v[224:225]
	v_add_f32_dpp v146, v146, v146 quad_perm:[2,3,0,1] row_mask:0xf bank_mask:0xf bound_ctrl:1
	v_add_f32 v150, v224, v225
	v_pk_mul_f32 v[242:243], v[242:243], v[250:251] op_sel_hi:[1,0]
	v_add_f32_dpp v146, v146, v146 row_half_mirror row_mask:0xf bank_mask:0xf bound_ctrl:1
	v_pk_mul_f32 v[244:245], v[244:245], v[250:251] op_sel_hi:[1,0]
	s_waitcnt lgkmcnt(6)
	v_add_f32_dpp v146, v146, v146 row_mirror row_mask:0xf bank_mask:0xf bound_ctrl:1
	v_pk_fma_f32 v[242:243], v[146:147], v[234:235], v[242:243] op_sel_hi:[0,1,1] neg_lo:[1,0,0] neg_hi:[1,0,0]
	v_pk_fma_f32 v[244:245], v[146:147], v[236:237], v[244:245] op_sel_hi:[0,1,1] neg_lo:[1,0,0] neg_hi:[1,0,0]
	v_pk_fma_f32 v[138:139], v[138:139], v[238:239], v[242:243]
	v_pk_fma_f32 v[140:141], v[140:141], v[240:241], v[244:245]
	v_pk_mul_f32 v[144:145], v[138:139], v[164:165]
	v_pk_fma_f32 v[144:145], v[140:141], v[166:167], v[144:145]
	v_add_f32 v146, v144, v145
	ds_read_b128 v[208:211], v10 offset:9216
	ds_read_b128 v[212:215], v10 offset:9472
	ds_read_b128 v[216:219], v10 offset:9728
	ds_read_b128 v[220:223], v10 offset:9984
	ds_read_b128 v[224:227], v10 offset:10240
	ds_read_b32 v228, v11 offset:9216
	v_add_f32_dpp v146, v146, v146 quad_perm:[1,0,3,2] row_mask:0xf bank_mask:0xf bound_ctrl:1
	v_pk_mul_f32 v[246:247], v[138:139], v[246:247]
	v_pk_fma_f32 v[246:247], v[140:141], v[248:249], v[246:247]
	v_add_f32_dpp v146, v146, v146 quad_perm:[2,3,0,1] row_mask:0xf bank_mask:0xf bound_ctrl:1
	v_add_f32 v151, v246, v247
	v_pk_mul_f32 v[176:177], v[176:177], v[184:185] op_sel_hi:[1,0]
	v_add_f32_dpp v146, v146, v146 row_half_mirror row_mask:0xf bank_mask:0xf bound_ctrl:1
	v_pk_mul_f32 v[178:179], v[178:179], v[184:185] op_sel_hi:[1,0]
	s_waitcnt lgkmcnt(6)
	v_add_f32_dpp v146, v146, v146 row_mirror row_mask:0xf bank_mask:0xf bound_ctrl:1
	v_pk_fma_f32 v[176:177], v[146:147], v[168:169], v[176:177] op_sel_hi:[0,1,1] neg_lo:[1,0,0] neg_hi:[1,0,0]
	v_pk_fma_f32 v[178:179], v[146:147], v[170:171], v[178:179] op_sel_hi:[0,1,1] neg_lo:[1,0,0] neg_hi:[1,0,0]
	v_pk_fma_f32 v[138:139], v[138:139], v[172:173], v[176:177]
	v_pk_fma_f32 v[140:141], v[140:141], v[174:175], v[178:179]
	v_pk_mul_f32 v[144:145], v[138:139], v[186:187]
	v_pk_fma_f32 v[144:145], v[140:141], v[188:189], v[144:145]
	v_add_f32 v146, v144, v145
	ds_read_b128 v[230:233], v10 offset:10752
	ds_read_b128 v[234:237], v10 offset:11008
	ds_read_b128 v[238:241], v10 offset:11264
	ds_read_b128 v[242:245], v10 offset:11520
	ds_read_b128 v[246:249], v10 offset:11776
	ds_read_b32 v250, v11 offset:10752
	v_add_f32_dpp v146, v146, v146 quad_perm:[1,0,3,2] row_mask:0xf bank_mask:0xf bound_ctrl:1
	v_pk_mul_f32 v[180:181], v[138:139], v[180:181]
	v_pk_fma_f32 v[180:181], v[140:141], v[182:183], v[180:181]
	v_add_f32_dpp v146, v146, v146 quad_perm:[2,3,0,1] row_mask:0xf bank_mask:0xf bound_ctrl:1
	v_add_f32 v152, v180, v181
	v_pk_mul_f32 v[198:199], v[198:199], v[206:207] op_sel_hi:[1,0]
	v_add_f32_dpp v146, v146, v146 row_half_mirror row_mask:0xf bank_mask:0xf bound_ctrl:1
	v_pk_mul_f32 v[200:201], v[200:201], v[206:207] op_sel_hi:[1,0]
	s_waitcnt lgkmcnt(6)
	v_add_f32_dpp v146, v146, v146 row_mirror row_mask:0xf bank_mask:0xf bound_ctrl:1
	v_pk_fma_f32 v[198:199], v[146:147], v[190:191], v[198:199] op_sel_hi:[0,1,1] neg_lo:[1,0,0] neg_hi:[1,0,0]
	v_pk_fma_f32 v[200:201], v[146:147], v[192:193], v[200:201] op_sel_hi:[0,1,1] neg_lo:[1,0,0] neg_hi:[1,0,0]
	v_pk_fma_f32 v[138:139], v[138:139], v[194:195], v[198:199]
	v_pk_fma_f32 v[140:141], v[140:141], v[196:197], v[200:201]
	v_pk_mul_f32 v[144:145], v[138:139], v[208:209]
	v_pk_fma_f32 v[144:145], v[140:141], v[210:211], v[144:145]
	v_add_f32 v146, v144, v145
	ds_read_b128 v[164:167], v10 offset:12288
	ds_read_b128 v[168:171], v10 offset:12544
	ds_read_b128 v[172:175], v10 offset:12800
	ds_read_b128 v[176:179], v10 offset:13056
	ds_read_b128 v[180:183], v10 offset:13312
	ds_read_b32 v184, v11 offset:12288
	v_add_f32_dpp v146, v146, v146 quad_perm:[1,0,3,2] row_mask:0xf bank_mask:0xf bound_ctrl:1
	v_pk_mul_f32 v[202:203], v[138:139], v[202:203]
	v_pk_fma_f32 v[202:203], v[140:141], v[204:205], v[202:203]
	v_add_f32_dpp v146, v146, v146 quad_perm:[2,3,0,1] row_mask:0xf bank_mask:0xf bound_ctrl:1
	v_add_f32 v153, v202, v203
	v_pk_mul_f32 v[220:221], v[220:221], v[228:229] op_sel_hi:[1,0]
	v_add_f32_dpp v146, v146, v146 row_half_mirror row_mask:0xf bank_mask:0xf bound_ctrl:1
	v_pk_mul_f32 v[222:223], v[222:223], v[228:229] op_sel_hi:[1,0]
	s_waitcnt lgkmcnt(6)
	v_add_f32_dpp v146, v146, v146 row_mirror row_mask:0xf bank_mask:0xf bound_ctrl:1
	v_pk_fma_f32 v[220:221], v[146:147], v[212:213], v[220:221] op_sel_hi:[0,1,1] neg_lo:[1,0,0] neg_hi:[1,0,0]
	v_pk_fma_f32 v[222:223], v[146:147], v[214:215], v[222:223] op_sel_hi:[0,1,1] neg_lo:[1,0,0] neg_hi:[1,0,0]
	v_pk_fma_f32 v[138:139], v[138:139], v[216:217], v[220:221]
	v_pk_fma_f32 v[140:141], v[140:141], v[218:219], v[222:223]
	v_pk_mul_f32 v[144:145], v[138:139], v[230:231]
	v_pk_fma_f32 v[144:145], v[140:141], v[232:233], v[144:145]
	v_add_f32 v146, v144, v145
	ds_read_b128 v[186:189], v10 offset:13824
	ds_read_b128 v[190:193], v10 offset:14080
	ds_read_b128 v[194:197], v10 offset:14336
	ds_read_b128 v[198:201], v10 offset:14592
	ds_read_b128 v[202:205], v10 offset:14848
	ds_read_b32 v206, v11 offset:13824
	v_add_f32_dpp v146, v146, v146 quad_perm:[1,0,3,2] row_mask:0xf bank_mask:0xf bound_ctrl:1
	v_pk_mul_f32 v[224:225], v[138:139], v[224:225]
	v_pk_fma_f32 v[224:225], v[140:141], v[226:227], v[224:225]
	v_add_f32_dpp v146, v146, v146 quad_perm:[2,3,0,1] row_mask:0xf bank_mask:0xf bound_ctrl:1
	v_add_f32 v154, v224, v225
	v_pk_mul_f32 v[242:243], v[242:243], v[250:251] op_sel_hi:[1,0]
	v_add_f32_dpp v146, v146, v146 row_half_mirror row_mask:0xf bank_mask:0xf bound_ctrl:1
	v_pk_mul_f32 v[244:245], v[244:245], v[250:251] op_sel_hi:[1,0]
	s_waitcnt lgkmcnt(6)
	v_add_f32_dpp v146, v146, v146 row_mirror row_mask:0xf bank_mask:0xf bound_ctrl:1
	v_pk_fma_f32 v[242:243], v[146:147], v[234:235], v[242:243] op_sel_hi:[0,1,1] neg_lo:[1,0,0] neg_hi:[1,0,0]
	v_pk_fma_f32 v[244:245], v[146:147], v[236:237], v[244:245] op_sel_hi:[0,1,1] neg_lo:[1,0,0] neg_hi:[1,0,0]
	v_pk_fma_f32 v[138:139], v[138:139], v[238:239], v[242:243]
	v_pk_fma_f32 v[140:141], v[140:141], v[240:241], v[244:245]
	v_pk_mul_f32 v[144:145], v[138:139], v[164:165]
	v_pk_fma_f32 v[144:145], v[140:141], v[166:167], v[144:145]
	v_add_f32 v146, v144, v145
	ds_read_b128 v[208:211], v10 offset:15360
	ds_read_b128 v[212:215], v10 offset:15616
	ds_read_b128 v[216:219], v10 offset:15872
	ds_read_b128 v[220:223], v10 offset:16128
	ds_read_b128 v[224:227], v10 offset:16384
	ds_read_b32 v228, v11 offset:15360
	v_add_f32_dpp v146, v146, v146 quad_perm:[1,0,3,2] row_mask:0xf bank_mask:0xf bound_ctrl:1
	v_pk_mul_f32 v[246:247], v[138:139], v[246:247]
	v_pk_fma_f32 v[246:247], v[140:141], v[248:249], v[246:247]
	v_add_f32_dpp v146, v146, v146 quad_perm:[2,3,0,1] row_mask:0xf bank_mask:0xf bound_ctrl:1
	v_add_f32 v155, v246, v247
	v_pk_mul_f32 v[176:177], v[176:177], v[184:185] op_sel_hi:[1,0]
	v_add_f32_dpp v146, v146, v146 row_half_mirror row_mask:0xf bank_mask:0xf bound_ctrl:1
	v_pk_mul_f32 v[178:179], v[178:179], v[184:185] op_sel_hi:[1,0]
	s_waitcnt lgkmcnt(6)
	v_add_f32_dpp v146, v146, v146 row_mirror row_mask:0xf bank_mask:0xf bound_ctrl:1
	v_pk_fma_f32 v[176:177], v[146:147], v[168:169], v[176:177] op_sel_hi:[0,1,1] neg_lo:[1,0,0] neg_hi:[1,0,0]
	v_pk_fma_f32 v[178:179], v[146:147], v[170:171], v[178:179] op_sel_hi:[0,1,1] neg_lo:[1,0,0] neg_hi:[1,0,0]
	v_pk_fma_f32 v[138:139], v[138:139], v[172:173], v[176:177]
	v_pk_fma_f32 v[140:141], v[140:141], v[174:175], v[178:179]
	v_pk_mul_f32 v[144:145], v[138:139], v[186:187]
	v_pk_fma_f32 v[144:145], v[140:141], v[188:189], v[144:145]
	v_add_f32 v146, v144, v145
	ds_read_b128 v[230:233], v10 offset:16896
	ds_read_b128 v[234:237], v10 offset:17152
	ds_read_b128 v[238:241], v10 offset:17408
	ds_read_b128 v[242:245], v10 offset:17664
	ds_read_b128 v[246:249], v10 offset:17920
	ds_read_b32 v250, v11 offset:16896
	v_add_f32_dpp v146, v146, v146 quad_perm:[1,0,3,2] row_mask:0xf bank_mask:0xf bound_ctrl:1
	v_pk_mul_f32 v[180:181], v[138:139], v[180:181]
	v_pk_fma_f32 v[180:181], v[140:141], v[182:183], v[180:181]
	v_add_f32_dpp v146, v146, v146 quad_perm:[2,3,0,1] row_mask:0xf bank_mask:0xf bound_ctrl:1
	v_add_f32 v156, v180, v181
	v_pk_mul_f32 v[198:199], v[198:199], v[206:207] op_sel_hi:[1,0]
	v_add_f32_dpp v146, v146, v146 row_half_mirror row_mask:0xf bank_mask:0xf bound_ctrl:1
	v_pk_mul_f32 v[200:201], v[200:201], v[206:207] op_sel_hi:[1,0]
	s_waitcnt lgkmcnt(6)
	v_add_f32_dpp v146, v146, v146 row_mirror row_mask:0xf bank_mask:0xf bound_ctrl:1
	v_pk_fma_f32 v[198:199], v[146:147], v[190:191], v[198:199] op_sel_hi:[0,1,1] neg_lo:[1,0,0] neg_hi:[1,0,0]
	v_pk_fma_f32 v[200:201], v[146:147], v[192:193], v[200:201] op_sel_hi:[0,1,1] neg_lo:[1,0,0] neg_hi:[1,0,0]
	v_pk_fma_f32 v[138:139], v[138:139], v[194:195], v[198:199]
	v_pk_fma_f32 v[140:141], v[140:141], v[196:197], v[200:201]
	v_pk_mul_f32 v[144:145], v[138:139], v[208:209]
	v_pk_fma_f32 v[144:145], v[140:141], v[210:211], v[144:145]
	v_add_f32 v146, v144, v145
	ds_read_b128 v[164:167], v10 offset:18432
	ds_read_b128 v[168:171], v10 offset:18688
	ds_read_b128 v[172:175], v10 offset:18944
	ds_read_b128 v[176:179], v10 offset:19200
	ds_read_b128 v[180:183], v10 offset:19456
	ds_read_b32 v184, v11 offset:18432
	v_add_f32_dpp v146, v146, v146 quad_perm:[1,0,3,2] row_mask:0xf bank_mask:0xf bound_ctrl:1
	v_pk_mul_f32 v[202:203], v[138:139], v[202:203]
	v_pk_fma_f32 v[202:203], v[140:141], v[204:205], v[202:203]
	v_add_f32_dpp v146, v146, v146 quad_perm:[2,3,0,1] row_mask:0xf bank_mask:0xf bound_ctrl:1
	v_add_f32 v157, v202, v203
	v_pk_mul_f32 v[220:221], v[220:221], v[228:229] op_sel_hi:[1,0]
	v_add_f32_dpp v146, v146, v146 row_half_mirror row_mask:0xf bank_mask:0xf bound_ctrl:1
	v_pk_mul_f32 v[222:223], v[222:223], v[228:229] op_sel_hi:[1,0]
	s_waitcnt lgkmcnt(6)
	v_add_f32_dpp v146, v146, v146 row_mirror row_mask:0xf bank_mask:0xf bound_ctrl:1
	v_pk_fma_f32 v[220:221], v[146:147], v[212:213], v[220:221] op_sel_hi:[0,1,1] neg_lo:[1,0,0] neg_hi:[1,0,0]
	v_pk_fma_f32 v[222:223], v[146:147], v[214:215], v[222:223] op_sel_hi:[0,1,1] neg_lo:[1,0,0] neg_hi:[1,0,0]
	v_pk_fma_f32 v[138:139], v[138:139], v[216:217], v[220:221]
	v_pk_fma_f32 v[140:141], v[140:141], v[218:219], v[222:223]
	v_pk_mul_f32 v[144:145], v[138:139], v[230:231]
	v_pk_fma_f32 v[144:145], v[140:141], v[232:233], v[144:145]
	v_add_f32 v146, v144, v145
	ds_read_b128 v[186:189], v10 offset:19968
	ds_read_b128 v[190:193], v10 offset:20224
	ds_read_b128 v[194:197], v10 offset:20480
	ds_read_b128 v[198:201], v10 offset:20736
	ds_read_b128 v[202:205], v10 offset:20992
	ds_read_b32 v206, v11 offset:19968
	v_add_f32_dpp v146, v146, v146 quad_perm:[1,0,3,2] row_mask:0xf bank_mask:0xf bound_ctrl:1
	v_pk_mul_f32 v[224:225], v[138:139], v[224:225]
	v_pk_fma_f32 v[224:225], v[140:141], v[226:227], v[224:225]
	v_add_f32_dpp v146, v146, v146 quad_perm:[2,3,0,1] row_mask:0xf bank_mask:0xf bound_ctrl:1
	v_add_f32 v158, v224, v225
	v_pk_mul_f32 v[242:243], v[242:243], v[250:251] op_sel_hi:[1,0]
	v_add_f32_dpp v146, v146, v146 row_half_mirror row_mask:0xf bank_mask:0xf bound_ctrl:1
	v_pk_mul_f32 v[244:245], v[244:245], v[250:251] op_sel_hi:[1,0]
	s_waitcnt lgkmcnt(6)
	v_add_f32_dpp v146, v146, v146 row_mirror row_mask:0xf bank_mask:0xf bound_ctrl:1
	v_pk_fma_f32 v[242:243], v[146:147], v[234:235], v[242:243] op_sel_hi:[0,1,1] neg_lo:[1,0,0] neg_hi:[1,0,0]
	v_pk_fma_f32 v[244:245], v[146:147], v[236:237], v[244:245] op_sel_hi:[0,1,1] neg_lo:[1,0,0] neg_hi:[1,0,0]
	v_pk_fma_f32 v[138:139], v[138:139], v[238:239], v[242:243]
	v_pk_fma_f32 v[140:141], v[140:141], v[240:241], v[244:245]
	v_pk_mul_f32 v[144:145], v[138:139], v[164:165]
	v_pk_fma_f32 v[144:145], v[140:141], v[166:167], v[144:145]
	v_add_f32 v146, v144, v145
	ds_read_b128 v[208:211], v10 offset:21504
	ds_read_b128 v[212:215], v10 offset:21760
	ds_read_b128 v[216:219], v10 offset:22016
	ds_read_b128 v[220:223], v10 offset:22272
	ds_read_b128 v[224:227], v10 offset:22528
	ds_read_b32 v228, v11 offset:21504
	v_add_f32_dpp v146, v146, v146 quad_perm:[1,0,3,2] row_mask:0xf bank_mask:0xf bound_ctrl:1
	v_pk_mul_f32 v[246:247], v[138:139], v[246:247]
	v_pk_fma_f32 v[246:247], v[140:141], v[248:249], v[246:247]
	v_add_f32_dpp v146, v146, v146 quad_perm:[2,3,0,1] row_mask:0xf bank_mask:0xf bound_ctrl:1
	v_add_f32 v159, v246, v247
	v_pk_mul_f32 v[176:177], v[176:177], v[184:185] op_sel_hi:[1,0]
	v_add_f32_dpp v146, v146, v146 row_half_mirror row_mask:0xf bank_mask:0xf bound_ctrl:1
	v_pk_mul_f32 v[178:179], v[178:179], v[184:185] op_sel_hi:[1,0]
	s_waitcnt lgkmcnt(6)
	v_add_f32_dpp v146, v146, v146 row_mirror row_mask:0xf bank_mask:0xf bound_ctrl:1
	v_pk_fma_f32 v[176:177], v[146:147], v[168:169], v[176:177] op_sel_hi:[0,1,1] neg_lo:[1,0,0] neg_hi:[1,0,0]
	v_pk_fma_f32 v[178:179], v[146:147], v[170:171], v[178:179] op_sel_hi:[0,1,1] neg_lo:[1,0,0] neg_hi:[1,0,0]
	v_pk_fma_f32 v[138:139], v[138:139], v[172:173], v[176:177]
	v_pk_fma_f32 v[140:141], v[140:141], v[174:175], v[178:179]
	v_pk_mul_f32 v[144:145], v[138:139], v[186:187]
	v_pk_fma_f32 v[144:145], v[140:141], v[188:189], v[144:145]
	v_add_f32 v146, v144, v145
	ds_read_b128 v[230:233], v10 offset:23040
	ds_read_b128 v[234:237], v10 offset:23296
	ds_read_b128 v[238:241], v10 offset:23552
	ds_read_b128 v[242:245], v10 offset:23808
	ds_read_b128 v[246:249], v10 offset:24064
	ds_read_b32 v250, v11 offset:23040
	v_add_f32_dpp v146, v146, v146 quad_perm:[1,0,3,2] row_mask:0xf bank_mask:0xf bound_ctrl:1
	v_pk_mul_f32 v[180:181], v[138:139], v[180:181]
	v_pk_fma_f32 v[180:181], v[140:141], v[182:183], v[180:181]
	v_add_f32_dpp v146, v146, v146 quad_perm:[2,3,0,1] row_mask:0xf bank_mask:0xf bound_ctrl:1
	v_add_f32 v160, v180, v181
	v_pk_mul_f32 v[198:199], v[198:199], v[206:207] op_sel_hi:[1,0]
	v_add_f32_dpp v146, v146, v146 row_half_mirror row_mask:0xf bank_mask:0xf bound_ctrl:1
	v_pk_mul_f32 v[200:201], v[200:201], v[206:207] op_sel_hi:[1,0]
	s_waitcnt lgkmcnt(6)
	v_add_f32_dpp v146, v146, v146 row_mirror row_mask:0xf bank_mask:0xf bound_ctrl:1
	v_pk_fma_f32 v[198:199], v[146:147], v[190:191], v[198:199] op_sel_hi:[0,1,1] neg_lo:[1,0,0] neg_hi:[1,0,0]
	v_pk_fma_f32 v[200:201], v[146:147], v[192:193], v[200:201] op_sel_hi:[0,1,1] neg_lo:[1,0,0] neg_hi:[1,0,0]
	v_pk_fma_f32 v[138:139], v[138:139], v[194:195], v[198:199]
	v_pk_fma_f32 v[140:141], v[140:141], v[196:197], v[200:201]
	v_pk_mul_f32 v[144:145], v[138:139], v[208:209]
	v_pk_fma_f32 v[144:145], v[140:141], v[210:211], v[144:145]
	v_add_f32 v146, v144, v145
	ds_read_b128 v[164:167], v10 offset:24576
	ds_read_b128 v[168:171], v10 offset:24832
	ds_read_b128 v[172:175], v10 offset:25088
	ds_read_b128 v[176:179], v10 offset:25344
	ds_read_b128 v[180:183], v10 offset:25600
	ds_read_b32 v184, v11 offset:24576
	v_add_f32_dpp v146, v146, v146 quad_perm:[1,0,3,2] row_mask:0xf bank_mask:0xf bound_ctrl:1
	v_pk_mul_f32 v[202:203], v[138:139], v[202:203]
	v_pk_fma_f32 v[202:203], v[140:141], v[204:205], v[202:203]
	v_add_f32_dpp v146, v146, v146 quad_perm:[2,3,0,1] row_mask:0xf bank_mask:0xf bound_ctrl:1
	v_add_f32 v161, v202, v203
	v_pk_mul_f32 v[220:221], v[220:221], v[228:229] op_sel_hi:[1,0]
	v_add_f32_dpp v146, v146, v146 row_half_mirror row_mask:0xf bank_mask:0xf bound_ctrl:1
	v_pk_mul_f32 v[222:223], v[222:223], v[228:229] op_sel_hi:[1,0]
	s_waitcnt lgkmcnt(6)
	v_add_f32_dpp v146, v146, v146 row_mirror row_mask:0xf bank_mask:0xf bound_ctrl:1
	v_pk_fma_f32 v[220:221], v[146:147], v[212:213], v[220:221] op_sel_hi:[0,1,1] neg_lo:[1,0,0] neg_hi:[1,0,0]
	v_pk_fma_f32 v[222:223], v[146:147], v[214:215], v[222:223] op_sel_hi:[0,1,1] neg_lo:[1,0,0] neg_hi:[1,0,0]
	v_pk_fma_f32 v[138:139], v[138:139], v[216:217], v[220:221]
	v_pk_fma_f32 v[140:141], v[140:141], v[218:219], v[222:223]
	v_pk_mul_f32 v[144:145], v[138:139], v[230:231]
	v_pk_fma_f32 v[144:145], v[140:141], v[232:233], v[144:145]
	v_add_f32 v146, v144, v145
	ds_read_b128 v[186:189], v10 offset:26112
	ds_read_b128 v[190:193], v10 offset:26368
	ds_read_b128 v[194:197], v10 offset:26624
	ds_read_b128 v[198:201], v10 offset:26880
	ds_read_b128 v[202:205], v10 offset:27136
	ds_read_b32 v206, v11 offset:26112
	v_add_f32_dpp v146, v146, v146 quad_perm:[1,0,3,2] row_mask:0xf bank_mask:0xf bound_ctrl:1
	v_pk_mul_f32 v[224:225], v[138:139], v[224:225]
	v_pk_fma_f32 v[224:225], v[140:141], v[226:227], v[224:225]
	v_add_f32_dpp v146, v146, v146 quad_perm:[2,3,0,1] row_mask:0xf bank_mask:0xf bound_ctrl:1
	v_add_f32 v162, v224, v225
	v_pk_mul_f32 v[242:243], v[242:243], v[250:251] op_sel_hi:[1,0]
	v_add_f32_dpp v146, v146, v146 row_half_mirror row_mask:0xf bank_mask:0xf bound_ctrl:1
	v_pk_mul_f32 v[244:245], v[244:245], v[250:251] op_sel_hi:[1,0]
	s_waitcnt lgkmcnt(6)
	v_add_f32_dpp v146, v146, v146 row_mirror row_mask:0xf bank_mask:0xf bound_ctrl:1
	v_pk_fma_f32 v[242:243], v[146:147], v[234:235], v[242:243] op_sel_hi:[0,1,1] neg_lo:[1,0,0] neg_hi:[1,0,0]
	v_pk_fma_f32 v[244:245], v[146:147], v[236:237], v[244:245] op_sel_hi:[0,1,1] neg_lo:[1,0,0] neg_hi:[1,0,0]
	v_pk_fma_f32 v[138:139], v[138:139], v[238:239], v[242:243]
	v_pk_fma_f32 v[140:141], v[140:141], v[240:241], v[244:245]
	v_pk_mul_f32 v[144:145], v[138:139], v[164:165]
	v_pk_fma_f32 v[144:145], v[140:141], v[166:167], v[144:145]
	v_add_f32 v146, v144, v145
	ds_read_b128 v[208:211], v10 offset:27648
	ds_read_b128 v[212:215], v10 offset:27904
	ds_read_b128 v[216:219], v10 offset:28160
	ds_read_b128 v[220:223], v10 offset:28416
	ds_read_b128 v[224:227], v10 offset:28672
	ds_read_b32 v228, v11 offset:27648
	v_add_f32_dpp v146, v146, v146 quad_perm:[1,0,3,2] row_mask:0xf bank_mask:0xf bound_ctrl:1
	v_pk_mul_f32 v[246:247], v[138:139], v[246:247]
	v_pk_fma_f32 v[246:247], v[140:141], v[248:249], v[246:247]
	v_add_f32_dpp v146, v146, v146 quad_perm:[2,3,0,1] row_mask:0xf bank_mask:0xf bound_ctrl:1
	v_add_f32 v163, v246, v247
	v_pk_mul_f32 v[176:177], v[176:177], v[184:185] op_sel_hi:[1,0]
	v_add_f32_dpp v146, v146, v146 row_half_mirror row_mask:0xf bank_mask:0xf bound_ctrl:1
	v_pk_mul_f32 v[178:179], v[178:179], v[184:185] op_sel_hi:[1,0]
	s_waitcnt lgkmcnt(6)
	v_add_f32_dpp v146, v146, v146 row_mirror row_mask:0xf bank_mask:0xf bound_ctrl:1
	v_pk_fma_f32 v[176:177], v[146:147], v[168:169], v[176:177] op_sel_hi:[0,1,1] neg_lo:[1,0,0] neg_hi:[1,0,0]
	v_pk_fma_f32 v[178:179], v[146:147], v[170:171], v[178:179] op_sel_hi:[0,1,1] neg_lo:[1,0,0] neg_hi:[1,0,0]
	v_pk_fma_f32 v[138:139], v[138:139], v[172:173], v[176:177]
	v_pk_fma_f32 v[140:141], v[140:141], v[174:175], v[178:179]
	v_pk_mul_f32 v[144:145], v[138:139], v[186:187]
	v_pk_fma_f32 v[144:145], v[140:141], v[188:189], v[144:145]
	v_add_f32 v146, v144, v145
	v_add_f32_dpp v230, v148, v148 row_mirror row_mask:0xf bank_mask:0x3 bound_ctrl:1
	v_add_f32_dpp v230, v156, v156 row_mirror row_mask:0xf bank_mask:0xc bound_ctrl:1
	v_add_f32_dpp v231, v149, v149 row_mirror row_mask:0xf bank_mask:0x3 bound_ctrl:1
	v_add_f32_dpp v231, v157, v157 row_mirror row_mask:0xf bank_mask:0xc bound_ctrl:1
	v_add_f32_dpp v232, v150, v150 row_mirror row_mask:0xf bank_mask:0x3 bound_ctrl:1
	v_add_f32_dpp v232, v158, v158 row_mirror row_mask:0xf bank_mask:0xc bound_ctrl:1
	v_add_f32_dpp v233, v151, v151 row_mirror row_mask:0xf bank_mask:0x3 bound_ctrl:1
	v_add_f32_dpp v233, v159, v159 row_mirror row_mask:0xf bank_mask:0xc bound_ctrl:1
	v_add_f32_dpp v234, v152, v152 row_mirror row_mask:0xf bank_mask:0x3 bound_ctrl:1
	v_add_f32_dpp v234, v160, v160 row_mirror row_mask:0xf bank_mask:0xc bound_ctrl:1
	v_add_f32_dpp v235, v153, v153 row_mirror row_mask:0xf bank_mask:0x3 bound_ctrl:1
	v_add_f32_dpp v235, v161, v161 row_mirror row_mask:0xf bank_mask:0xc bound_ctrl:1
	v_add_f32_dpp v236, v154, v154 row_mirror row_mask:0xf bank_mask:0x3 bound_ctrl:1
	v_add_f32_dpp v236, v162, v162 row_mirror row_mask:0xf bank_mask:0xc bound_ctrl:1
	v_add_f32_dpp v237, v155, v155 row_mirror row_mask:0xf bank_mask:0x3 bound_ctrl:1
	v_add_f32_dpp v237, v163, v163 row_mirror row_mask:0xf bank_mask:0xc bound_ctrl:1
	v_add_f32_dpp v238, v230, v230 row_half_mirror row_mask:0xf bank_mask:0x5 bound_ctrl:1
	v_add_f32_dpp v238, v234, v234 row_half_mirror row_mask:0xf bank_mask:0xa bound_ctrl:1
	v_add_f32_dpp v239, v231, v231 row_half_mirror row_mask:0xf bank_mask:0x5 bound_ctrl:1
	v_add_f32_dpp v239, v235, v235 row_half_mirror row_mask:0xf bank_mask:0xa bound_ctrl:1
	v_add_f32_dpp v240, v232, v232 row_half_mirror row_mask:0xf bank_mask:0x5 bound_ctrl:1
	v_add_f32_dpp v240, v236, v236 row_half_mirror row_mask:0xf bank_mask:0xa bound_ctrl:1
	v_add_f32_dpp v241, v233, v233 row_half_mirror row_mask:0xf bank_mask:0x5 bound_ctrl:1
	v_add_f32_dpp v241, v237, v237 row_half_mirror row_mask:0xf bank_mask:0xa bound_ctrl:1
	s_mov_b32 vcc_lo, 0xcccccccc
	s_mov_b32 vcc_hi, 0xcccccccc
	v_cndmask_b32 v244, v240, v238, vcc
	v_cndmask_b32 v245, v241, v239, vcc
	v_cndmask_b32 v242, v238, v240, vcc
	v_cndmask_b32 v243, v239, v241, vcc
	v_add_f32_dpp v242, v244, v242 quad_perm:[2,3,0,1] row_mask:0xf bank_mask:0xf bound_ctrl:1
	v_add_f32_dpp v243, v245, v243 quad_perm:[2,3,0,1] row_mask:0xf bank_mask:0xf bound_ctrl:1
	s_mov_b32 vcc_lo, 0xaaaaaaaa
	s_mov_b32 vcc_hi, 0xaaaaaaaa
	v_cndmask_b32 v244, v243, v242, vcc
	v_cndmask_b32 v245, v242, v243, vcc
	s_nop 0
	v_add_f32_dpp v18, v244, v245 quad_perm:[1,0,3,2] row_mask:0xf bank_mask:0xf bound_ctrl:1
	ds_read_b128 v[230:233], v10 offset:29184
	ds_read_b128 v[234:237], v10 offset:29440
	ds_read_b128 v[238:241], v10 offset:29696
	ds_read_b128 v[242:245], v10 offset:29952
	ds_read_b128 v[246:249], v10 offset:30208
	ds_read_b32 v250, v11 offset:29184
	v_add_f32_dpp v146, v146, v146 quad_perm:[1,0,3,2] row_mask:0xf bank_mask:0xf bound_ctrl:1
	v_pk_mul_f32 v[180:181], v[138:139], v[180:181]
	v_pk_fma_f32 v[180:181], v[140:141], v[182:183], v[180:181]
	v_add_f32_dpp v146, v146, v146 quad_perm:[2,3,0,1] row_mask:0xf bank_mask:0xf bound_ctrl:1
	v_add_f32 v148, v180, v181
	v_pk_mul_f32 v[198:199], v[198:199], v[206:207] op_sel_hi:[1,0]
	v_add_f32_dpp v146, v146, v146 row_half_mirror row_mask:0xf bank_mask:0xf bound_ctrl:1
	v_pk_mul_f32 v[200:201], v[200:201], v[206:207] op_sel_hi:[1,0]
	s_waitcnt lgkmcnt(6)
	v_add_f32_dpp v146, v146, v146 row_mirror row_mask:0xf bank_mask:0xf bound_ctrl:1
	v_pk_fma_f32 v[198:199], v[146:147], v[190:191], v[198:199] op_sel_hi:[0,1,1] neg_lo:[1,0,0] neg_hi:[1,0,0]
	v_pk_fma_f32 v[200:201], v[146:147], v[192:193], v[200:201] op_sel_hi:[0,1,1] neg_lo:[1,0,0] neg_hi:[1,0,0]
	v_pk_fma_f32 v[138:139], v[138:139], v[194:195], v[198:199]
	v_pk_fma_f32 v[140:141], v[140:141], v[196:197], v[200:201]
	v_pk_mul_f32 v[144:145], v[138:139], v[208:209]
	v_pk_fma_f32 v[144:145], v[140:141], v[210:211], v[144:145]
	v_add_f32 v146, v144, v145
	ds_read_b128 v[164:167], v10 offset:30720
	ds_read_b128 v[168:171], v10 offset:30976
	ds_read_b128 v[172:175], v10 offset:31232
	ds_read_b128 v[176:179], v10 offset:31488
	ds_read_b128 v[180:183], v10 offset:31744
	ds_read_b32 v184, v11 offset:30720
	v_add_f32_dpp v146, v146, v146 quad_perm:[1,0,3,2] row_mask:0xf bank_mask:0xf bound_ctrl:1
	v_pk_mul_f32 v[202:203], v[138:139], v[202:203]
	v_pk_fma_f32 v[202:203], v[140:141], v[204:205], v[202:203]
	v_add_f32_dpp v146, v146, v146 quad_perm:[2,3,0,1] row_mask:0xf bank_mask:0xf bound_ctrl:1
	v_add_f32 v149, v202, v203
	v_pk_mul_f32 v[220:221], v[220:221], v[228:229] op_sel_hi:[1,0]
	v_add_f32_dpp v146, v146, v146 row_half_mirror row_mask:0xf bank_mask:0xf bound_ctrl:1
	v_pk_mul_f32 v[222:223], v[222:223], v[228:229] op_sel_hi:[1,0]
	s_waitcnt lgkmcnt(6)
	v_add_f32_dpp v146, v146, v146 row_mirror row_mask:0xf bank_mask:0xf bound_ctrl:1
	v_pk_fma_f32 v[220:221], v[146:147], v[212:213], v[220:221] op_sel_hi:[0,1,1] neg_lo:[1,0,0] neg_hi:[1,0,0]
	v_pk_fma_f32 v[222:223], v[146:147], v[214:215], v[222:223] op_sel_hi:[0,1,1] neg_lo:[1,0,0] neg_hi:[1,0,0]
	v_pk_fma_f32 v[138:139], v[138:139], v[216:217], v[220:221]
	v_pk_fma_f32 v[140:141], v[140:141], v[218:219], v[222:223]
	v_pk_mul_f32 v[144:145], v[138:139], v[230:231]
	v_pk_fma_f32 v[144:145], v[140:141], v[232:233], v[144:145]
	v_add_f32 v146, v144, v145
	ds_read_b128 v[186:189], v10 offset:32256
	ds_read_b128 v[190:193], v10 offset:32512
	ds_read_b128 v[194:197], v10 offset:32768
	ds_read_b128 v[198:201], v10 offset:33024
	ds_read_b128 v[202:205], v10 offset:33280
	ds_read_b32 v206, v11 offset:32256
	v_add_f32_dpp v146, v146, v146 quad_perm:[1,0,3,2] row_mask:0xf bank_mask:0xf bound_ctrl:1
	v_pk_mul_f32 v[224:225], v[138:139], v[224:225]
	v_pk_fma_f32 v[224:225], v[140:141], v[226:227], v[224:225]
	v_add_f32_dpp v146, v146, v146 quad_perm:[2,3,0,1] row_mask:0xf bank_mask:0xf bound_ctrl:1
	v_add_f32 v150, v224, v225
	v_pk_mul_f32 v[242:243], v[242:243], v[250:251] op_sel_hi:[1,0]
	v_add_f32_dpp v146, v146, v146 row_half_mirror row_mask:0xf bank_mask:0xf bound_ctrl:1
	v_pk_mul_f32 v[244:245], v[244:245], v[250:251] op_sel_hi:[1,0]
	s_waitcnt lgkmcnt(6)
	v_add_f32_dpp v146, v146, v146 row_mirror row_mask:0xf bank_mask:0xf bound_ctrl:1
	v_pk_fma_f32 v[242:243], v[146:147], v[234:235], v[242:243] op_sel_hi:[0,1,1] neg_lo:[1,0,0] neg_hi:[1,0,0]
	v_pk_fma_f32 v[244:245], v[146:147], v[236:237], v[244:245] op_sel_hi:[0,1,1] neg_lo:[1,0,0] neg_hi:[1,0,0]
	v_pk_fma_f32 v[138:139], v[138:139], v[238:239], v[242:243]
	v_pk_fma_f32 v[140:141], v[140:141], v[240:241], v[244:245]
	v_pk_mul_f32 v[144:145], v[138:139], v[164:165]
	v_pk_fma_f32 v[144:145], v[140:141], v[166:167], v[144:145]
	v_add_f32 v146, v144, v145
	ds_read_b128 v[208:211], v10 offset:33792
	ds_read_b128 v[212:215], v10 offset:34048
	ds_read_b128 v[216:219], v10 offset:34304
	ds_read_b128 v[220:223], v10 offset:34560
	ds_read_b128 v[224:227], v10 offset:34816
	ds_read_b32 v228, v11 offset:33792
	v_add_f32_dpp v146, v146, v146 quad_perm:[1,0,3,2] row_mask:0xf bank_mask:0xf bound_ctrl:1
	v_pk_mul_f32 v[246:247], v[138:139], v[246:247]
	v_pk_fma_f32 v[246:247], v[140:141], v[248:249], v[246:247]
	v_add_f32_dpp v146, v146, v146 quad_perm:[2,3,0,1] row_mask:0xf bank_mask:0xf bound_ctrl:1
	v_add_f32 v151, v246, v247
	v_pk_mul_f32 v[176:177], v[176:177], v[184:185] op_sel_hi:[1,0]
	v_add_f32_dpp v146, v146, v146 row_half_mirror row_mask:0xf bank_mask:0xf bound_ctrl:1
	v_pk_mul_f32 v[178:179], v[178:179], v[184:185] op_sel_hi:[1,0]
	s_waitcnt lgkmcnt(6)
	v_add_f32_dpp v146, v146, v146 row_mirror row_mask:0xf bank_mask:0xf bound_ctrl:1
	v_pk_fma_f32 v[176:177], v[146:147], v[168:169], v[176:177] op_sel_hi:[0,1,1] neg_lo:[1,0,0] neg_hi:[1,0,0]
	v_pk_fma_f32 v[178:179], v[146:147], v[170:171], v[178:179] op_sel_hi:[0,1,1] neg_lo:[1,0,0] neg_hi:[1,0,0]
	v_pk_fma_f32 v[138:139], v[138:139], v[172:173], v[176:177]
	v_pk_fma_f32 v[140:141], v[140:141], v[174:175], v[178:179]
	v_pk_mul_f32 v[144:145], v[138:139], v[186:187]
	v_pk_fma_f32 v[144:145], v[140:141], v[188:189], v[144:145]
	v_add_f32 v146, v144, v145
	ds_read_b128 v[230:233], v10 offset:35328
	ds_read_b128 v[234:237], v10 offset:35584
	ds_read_b128 v[238:241], v10 offset:35840
	ds_read_b128 v[242:245], v10 offset:36096
	ds_read_b128 v[246:249], v10 offset:36352
	ds_read_b32 v250, v11 offset:35328
	v_add_f32_dpp v146, v146, v146 quad_perm:[1,0,3,2] row_mask:0xf bank_mask:0xf bound_ctrl:1
	v_pk_mul_f32 v[180:181], v[138:139], v[180:181]
	v_pk_fma_f32 v[180:181], v[140:141], v[182:183], v[180:181]
	v_add_f32_dpp v146, v146, v146 quad_perm:[2,3,0,1] row_mask:0xf bank_mask:0xf bound_ctrl:1
	v_add_f32 v152, v180, v181
	v_pk_mul_f32 v[198:199], v[198:199], v[206:207] op_sel_hi:[1,0]
	v_add_f32_dpp v146, v146, v146 row_half_mirror row_mask:0xf bank_mask:0xf bound_ctrl:1
	v_pk_mul_f32 v[200:201], v[200:201], v[206:207] op_sel_hi:[1,0]
	s_waitcnt lgkmcnt(6)
	v_add_f32_dpp v146, v146, v146 row_mirror row_mask:0xf bank_mask:0xf bound_ctrl:1
	v_pk_fma_f32 v[198:199], v[146:147], v[190:191], v[198:199] op_sel_hi:[0,1,1] neg_lo:[1,0,0] neg_hi:[1,0,0]
	v_pk_fma_f32 v[200:201], v[146:147], v[192:193], v[200:201] op_sel_hi:[0,1,1] neg_lo:[1,0,0] neg_hi:[1,0,0]
	v_pk_fma_f32 v[138:139], v[138:139], v[194:195], v[198:199]
	v_pk_fma_f32 v[140:141], v[140:141], v[196:197], v[200:201]
	v_pk_mul_f32 v[144:145], v[138:139], v[208:209]
	v_pk_fma_f32 v[144:145], v[140:141], v[210:211], v[144:145]
	v_add_f32 v146, v144, v145
	ds_read_b128 v[164:167], v10 offset:36864
	ds_read_b128 v[168:171], v10 offset:37120
	ds_read_b128 v[172:175], v10 offset:37376
	ds_read_b128 v[176:179], v10 offset:37632
	ds_read_b128 v[180:183], v10 offset:37888
	ds_read_b32 v184, v11 offset:36864
	v_add_f32_dpp v146, v146, v146 quad_perm:[1,0,3,2] row_mask:0xf bank_mask:0xf bound_ctrl:1
	v_pk_mul_f32 v[202:203], v[138:139], v[202:203]
	v_pk_fma_f32 v[202:203], v[140:141], v[204:205], v[202:203]
	v_add_f32_dpp v146, v146, v146 quad_perm:[2,3,0,1] row_mask:0xf bank_mask:0xf bound_ctrl:1
	v_add_f32 v153, v202, v203
	v_pk_mul_f32 v[220:221], v[220:221], v[228:229] op_sel_hi:[1,0]
	v_add_f32_dpp v146, v146, v146 row_half_mirror row_mask:0xf bank_mask:0xf bound_ctrl:1
	v_pk_mul_f32 v[222:223], v[222:223], v[228:229] op_sel_hi:[1,0]
	s_waitcnt lgkmcnt(6)
	v_add_f32_dpp v146, v146, v146 row_mirror row_mask:0xf bank_mask:0xf bound_ctrl:1
	v_pk_fma_f32 v[220:221], v[146:147], v[212:213], v[220:221] op_sel_hi:[0,1,1] neg_lo:[1,0,0] neg_hi:[1,0,0]
	v_pk_fma_f32 v[222:223], v[146:147], v[214:215], v[222:223] op_sel_hi:[0,1,1] neg_lo:[1,0,0] neg_hi:[1,0,0]
	v_pk_fma_f32 v[138:139], v[138:139], v[216:217], v[220:221]
	v_pk_fma_f32 v[140:141], v[140:141], v[218:219], v[222:223]
	v_pk_mul_f32 v[144:145], v[138:139], v[230:231]
	v_pk_fma_f32 v[144:145], v[140:141], v[232:233], v[144:145]
	v_add_f32 v146, v144, v145
	ds_read_b128 v[186:189], v10 offset:38400
	ds_read_b128 v[190:193], v10 offset:38656
	ds_read_b128 v[194:197], v10 offset:38912
	ds_read_b128 v[198:201], v10 offset:39168
	ds_read_b128 v[202:205], v10 offset:39424
	ds_read_b32 v206, v11 offset:38400
	v_add_f32_dpp v146, v146, v146 quad_perm:[1,0,3,2] row_mask:0xf bank_mask:0xf bound_ctrl:1
	v_pk_mul_f32 v[224:225], v[138:139], v[224:225]
	v_pk_fma_f32 v[224:225], v[140:141], v[226:227], v[224:225]
	v_add_f32_dpp v146, v146, v146 quad_perm:[2,3,0,1] row_mask:0xf bank_mask:0xf bound_ctrl:1
	v_add_f32 v154, v224, v225
	v_pk_mul_f32 v[242:243], v[242:243], v[250:251] op_sel_hi:[1,0]
	v_add_f32_dpp v146, v146, v146 row_half_mirror row_mask:0xf bank_mask:0xf bound_ctrl:1
	v_pk_mul_f32 v[244:245], v[244:245], v[250:251] op_sel_hi:[1,0]
	s_waitcnt lgkmcnt(6)
	v_add_f32_dpp v146, v146, v146 row_mirror row_mask:0xf bank_mask:0xf bound_ctrl:1
	v_pk_fma_f32 v[242:243], v[146:147], v[234:235], v[242:243] op_sel_hi:[0,1,1] neg_lo:[1,0,0] neg_hi:[1,0,0]
	v_pk_fma_f32 v[244:245], v[146:147], v[236:237], v[244:245] op_sel_hi:[0,1,1] neg_lo:[1,0,0] neg_hi:[1,0,0]
	v_pk_fma_f32 v[138:139], v[138:139], v[238:239], v[242:243]
	v_pk_fma_f32 v[140:141], v[140:141], v[240:241], v[244:245]
	v_pk_mul_f32 v[144:145], v[138:139], v[164:165]
	v_pk_fma_f32 v[144:145], v[140:141], v[166:167], v[144:145]
	v_add_f32 v146, v144, v145
	ds_read_b128 v[208:211], v10 offset:39936
	ds_read_b128 v[212:215], v10 offset:40192
	ds_read_b128 v[216:219], v10 offset:40448
	ds_read_b128 v[220:223], v10 offset:40704
	ds_read_b128 v[224:227], v10 offset:40960
	ds_read_b32 v228, v11 offset:39936
	v_add_f32_dpp v146, v146, v146 quad_perm:[1,0,3,2] row_mask:0xf bank_mask:0xf bound_ctrl:1
	v_pk_mul_f32 v[246:247], v[138:139], v[246:247]
	v_pk_fma_f32 v[246:247], v[140:141], v[248:249], v[246:247]
	v_add_f32_dpp v146, v146, v146 quad_perm:[2,3,0,1] row_mask:0xf bank_mask:0xf bound_ctrl:1
	v_add_f32 v155, v246, v247
	v_pk_mul_f32 v[176:177], v[176:177], v[184:185] op_sel_hi:[1,0]
	v_add_f32_dpp v146, v146, v146 row_half_mirror row_mask:0xf bank_mask:0xf bound_ctrl:1
	v_pk_mul_f32 v[178:179], v[178:179], v[184:185] op_sel_hi:[1,0]
	s_waitcnt lgkmcnt(6)
	v_add_f32_dpp v146, v146, v146 row_mirror row_mask:0xf bank_mask:0xf bound_ctrl:1
	v_pk_fma_f32 v[176:177], v[146:147], v[168:169], v[176:177] op_sel_hi:[0,1,1] neg_lo:[1,0,0] neg_hi:[1,0,0]
	v_pk_fma_f32 v[178:179], v[146:147], v[170:171], v[178:179] op_sel_hi:[0,1,1] neg_lo:[1,0,0] neg_hi:[1,0,0]
	v_pk_fma_f32 v[138:139], v[138:139], v[172:173], v[176:177]
	v_pk_fma_f32 v[140:141], v[140:141], v[174:175], v[178:179]
	v_pk_mul_f32 v[144:145], v[138:139], v[186:187]
	v_pk_fma_f32 v[144:145], v[140:141], v[188:189], v[144:145]
	v_add_f32 v146, v144, v145
	ds_read_b128 v[230:233], v10 offset:41472
	ds_read_b128 v[234:237], v10 offset:41728
	ds_read_b128 v[238:241], v10 offset:41984
	ds_read_b128 v[242:245], v10 offset:42240
	ds_read_b128 v[246:249], v10 offset:42496
	ds_read_b32 v250, v11 offset:41472
	v_add_f32_dpp v146, v146, v146 quad_perm:[1,0,3,2] row_mask:0xf bank_mask:0xf bound_ctrl:1
	v_pk_mul_f32 v[180:181], v[138:139], v[180:181]
	v_pk_fma_f32 v[180:181], v[140:141], v[182:183], v[180:181]
	v_add_f32_dpp v146, v146, v146 quad_perm:[2,3,0,1] row_mask:0xf bank_mask:0xf bound_ctrl:1
	v_add_f32 v156, v180, v181
	v_pk_mul_f32 v[198:199], v[198:199], v[206:207] op_sel_hi:[1,0]
	v_add_f32_dpp v146, v146, v146 row_half_mirror row_mask:0xf bank_mask:0xf bound_ctrl:1
	v_pk_mul_f32 v[200:201], v[200:201], v[206:207] op_sel_hi:[1,0]
	s_waitcnt lgkmcnt(6)
	v_add_f32_dpp v146, v146, v146 row_mirror row_mask:0xf bank_mask:0xf bound_ctrl:1
	v_pk_fma_f32 v[198:199], v[146:147], v[190:191], v[198:199] op_sel_hi:[0,1,1] neg_lo:[1,0,0] neg_hi:[1,0,0]
	v_pk_fma_f32 v[200:201], v[146:147], v[192:193], v[200:201] op_sel_hi:[0,1,1] neg_lo:[1,0,0] neg_hi:[1,0,0]
	v_pk_fma_f32 v[138:139], v[138:139], v[194:195], v[198:199]
	v_pk_fma_f32 v[140:141], v[140:141], v[196:197], v[200:201]
	v_pk_mul_f32 v[144:145], v[138:139], v[208:209]
	v_pk_fma_f32 v[144:145], v[140:141], v[210:211], v[144:145]
	v_add_f32 v146, v144, v145
	ds_read_b128 v[164:167], v10 offset:43008
	ds_read_b128 v[168:171], v10 offset:43264
	ds_read_b128 v[172:175], v10 offset:43520
	ds_read_b128 v[176:179], v10 offset:43776
	ds_read_b128 v[180:183], v10 offset:44032
	ds_read_b32 v184, v11 offset:43008
	v_add_f32_dpp v146, v146, v146 quad_perm:[1,0,3,2] row_mask:0xf bank_mask:0xf bound_ctrl:1
	v_pk_mul_f32 v[202:203], v[138:139], v[202:203]
	v_pk_fma_f32 v[202:203], v[140:141], v[204:205], v[202:203]
	v_add_f32_dpp v146, v146, v146 quad_perm:[2,3,0,1] row_mask:0xf bank_mask:0xf bound_ctrl:1
	v_add_f32 v157, v202, v203
	v_pk_mul_f32 v[220:221], v[220:221], v[228:229] op_sel_hi:[1,0]
	v_add_f32_dpp v146, v146, v146 row_half_mirror row_mask:0xf bank_mask:0xf bound_ctrl:1
	v_pk_mul_f32 v[222:223], v[222:223], v[228:229] op_sel_hi:[1,0]
	s_waitcnt lgkmcnt(6)
	v_add_f32_dpp v146, v146, v146 row_mirror row_mask:0xf bank_mask:0xf bound_ctrl:1
	v_pk_fma_f32 v[220:221], v[146:147], v[212:213], v[220:221] op_sel_hi:[0,1,1] neg_lo:[1,0,0] neg_hi:[1,0,0]
	v_pk_fma_f32 v[222:223], v[146:147], v[214:215], v[222:223] op_sel_hi:[0,1,1] neg_lo:[1,0,0] neg_hi:[1,0,0]
	v_pk_fma_f32 v[138:139], v[138:139], v[216:217], v[220:221]
	v_pk_fma_f32 v[140:141], v[140:141], v[218:219], v[222:223]
	v_pk_mul_f32 v[144:145], v[138:139], v[230:231]
	v_pk_fma_f32 v[144:145], v[140:141], v[232:233], v[144:145]
	v_add_f32 v146, v144, v145
	ds_read_b128 v[186:189], v10 offset:44544
	ds_read_b128 v[190:193], v10 offset:44800
	ds_read_b128 v[194:197], v10 offset:45056
	ds_read_b128 v[198:201], v10 offset:45312
	ds_read_b128 v[202:205], v10 offset:45568
	ds_read_b32 v206, v11 offset:44544
	v_add_f32_dpp v146, v146, v146 quad_perm:[1,0,3,2] row_mask:0xf bank_mask:0xf bound_ctrl:1
	v_pk_mul_f32 v[224:225], v[138:139], v[224:225]
	v_pk_fma_f32 v[224:225], v[140:141], v[226:227], v[224:225]
	v_add_f32_dpp v146, v146, v146 quad_perm:[2,3,0,1] row_mask:0xf bank_mask:0xf bound_ctrl:1
	v_add_f32 v158, v224, v225
	v_pk_mul_f32 v[242:243], v[242:243], v[250:251] op_sel_hi:[1,0]
	v_add_f32_dpp v146, v146, v146 row_half_mirror row_mask:0xf bank_mask:0xf bound_ctrl:1
	v_pk_mul_f32 v[244:245], v[244:245], v[250:251] op_sel_hi:[1,0]
	s_waitcnt lgkmcnt(6)
	v_add_f32_dpp v146, v146, v146 row_mirror row_mask:0xf bank_mask:0xf bound_ctrl:1
	v_pk_fma_f32 v[242:243], v[146:147], v[234:235], v[242:243] op_sel_hi:[0,1,1] neg_lo:[1,0,0] neg_hi:[1,0,0]
	v_pk_fma_f32 v[244:245], v[146:147], v[236:237], v[244:245] op_sel_hi:[0,1,1] neg_lo:[1,0,0] neg_hi:[1,0,0]
	v_pk_fma_f32 v[138:139], v[138:139], v[238:239], v[242:243]
	v_pk_fma_f32 v[140:141], v[140:141], v[240:241], v[244:245]
	v_pk_mul_f32 v[144:145], v[138:139], v[164:165]
	v_pk_fma_f32 v[144:145], v[140:141], v[166:167], v[144:145]
	v_add_f32 v146, v144, v145
	ds_read_b128 v[208:211], v10 offset:46080
	ds_read_b128 v[212:215], v10 offset:46336
	ds_read_b128 v[216:219], v10 offset:46592
	ds_read_b128 v[220:223], v10 offset:46848
	ds_read_b128 v[224:227], v10 offset:47104
	ds_read_b32 v228, v11 offset:46080
	v_add_f32_dpp v146, v146, v146 quad_perm:[1,0,3,2] row_mask:0xf bank_mask:0xf bound_ctrl:1
	v_pk_mul_f32 v[246:247], v[138:139], v[246:247]
	v_pk_fma_f32 v[246:247], v[140:141], v[248:249], v[246:247]
	v_add_f32_dpp v146, v146, v146 quad_perm:[2,3,0,1] row_mask:0xf bank_mask:0xf bound_ctrl:1
	v_add_f32 v159, v246, v247
	v_pk_mul_f32 v[176:177], v[176:177], v[184:185] op_sel_hi:[1,0]
	v_add_f32_dpp v146, v146, v146 row_half_mirror row_mask:0xf bank_mask:0xf bound_ctrl:1
	v_pk_mul_f32 v[178:179], v[178:179], v[184:185] op_sel_hi:[1,0]
	s_waitcnt lgkmcnt(6)
	v_add_f32_dpp v146, v146, v146 row_mirror row_mask:0xf bank_mask:0xf bound_ctrl:1
	v_pk_fma_f32 v[176:177], v[146:147], v[168:169], v[176:177] op_sel_hi:[0,1,1] neg_lo:[1,0,0] neg_hi:[1,0,0]
	v_pk_fma_f32 v[178:179], v[146:147], v[170:171], v[178:179] op_sel_hi:[0,1,1] neg_lo:[1,0,0] neg_hi:[1,0,0]
	v_pk_fma_f32 v[138:139], v[138:139], v[172:173], v[176:177]
	v_pk_fma_f32 v[140:141], v[140:141], v[174:175], v[178:179]
	v_pk_mul_f32 v[144:145], v[138:139], v[186:187]
	v_pk_fma_f32 v[144:145], v[140:141], v[188:189], v[144:145]
	v_add_f32 v146, v144, v145
	ds_read_b128 v[230:233], v10 offset:47616
	ds_read_b128 v[234:237], v10 offset:47872
	ds_read_b128 v[238:241], v10 offset:48128
	ds_read_b128 v[242:245], v10 offset:48384
	ds_read_b128 v[246:249], v10 offset:48640
	ds_read_b32 v250, v11 offset:47616
	v_add_f32_dpp v146, v146, v146 quad_perm:[1,0,3,2] row_mask:0xf bank_mask:0xf bound_ctrl:1
	v_pk_mul_f32 v[180:181], v[138:139], v[180:181]
	v_pk_fma_f32 v[180:181], v[140:141], v[182:183], v[180:181]
	v_add_f32_dpp v146, v146, v146 quad_perm:[2,3,0,1] row_mask:0xf bank_mask:0xf bound_ctrl:1
	v_add_f32 v160, v180, v181
	v_pk_mul_f32 v[198:199], v[198:199], v[206:207] op_sel_hi:[1,0]
	v_add_f32_dpp v146, v146, v146 row_half_mirror row_mask:0xf bank_mask:0xf bound_ctrl:1
	v_pk_mul_f32 v[200:201], v[200:201], v[206:207] op_sel_hi:[1,0]
	s_waitcnt lgkmcnt(6)
	v_add_f32_dpp v146, v146, v146 row_mirror row_mask:0xf bank_mask:0xf bound_ctrl:1
	v_pk_fma_f32 v[198:199], v[146:147], v[190:191], v[198:199] op_sel_hi:[0,1,1] neg_lo:[1,0,0] neg_hi:[1,0,0]
	v_pk_fma_f32 v[200:201], v[146:147], v[192:193], v[200:201] op_sel_hi:[0,1,1] neg_lo:[1,0,0] neg_hi:[1,0,0]
	v_pk_fma_f32 v[138:139], v[138:139], v[194:195], v[198:199]
	v_pk_fma_f32 v[140:141], v[140:141], v[196:197], v[200:201]
	v_pk_mul_f32 v[144:145], v[138:139], v[208:209]
	v_pk_fma_f32 v[144:145], v[140:141], v[210:211], v[144:145]
	v_add_f32 v146, v144, v145
	s_nop 1
	v_add_f32_dpp v146, v146, v146 quad_perm:[1,0,3,2] row_mask:0xf bank_mask:0xf bound_ctrl:1
	v_pk_mul_f32 v[202:203], v[138:139], v[202:203]
	v_pk_fma_f32 v[202:203], v[140:141], v[204:205], v[202:203]
	v_add_f32_dpp v146, v146, v146 quad_perm:[2,3,0,1] row_mask:0xf bank_mask:0xf bound_ctrl:1
	v_add_f32 v161, v202, v203
	v_pk_mul_f32 v[220:221], v[220:221], v[228:229] op_sel_hi:[1,0]
	v_add_f32_dpp v146, v146, v146 row_half_mirror row_mask:0xf bank_mask:0xf bound_ctrl:1
	v_pk_mul_f32 v[222:223], v[222:223], v[228:229] op_sel_hi:[1,0]
	s_waitcnt lgkmcnt(0)
	v_add_f32_dpp v146, v146, v146 row_mirror row_mask:0xf bank_mask:0xf bound_ctrl:1
	v_pk_fma_f32 v[220:221], v[146:147], v[212:213], v[220:221] op_sel_hi:[0,1,1] neg_lo:[1,0,0] neg_hi:[1,0,0]
	v_pk_fma_f32 v[222:223], v[146:147], v[214:215], v[222:223] op_sel_hi:[0,1,1] neg_lo:[1,0,0] neg_hi:[1,0,0]
	v_pk_fma_f32 v[138:139], v[138:139], v[216:217], v[220:221]
	v_pk_fma_f32 v[140:141], v[140:141], v[218:219], v[222:223]
	v_pk_mul_f32 v[144:145], v[138:139], v[230:231]
	v_pk_fma_f32 v[144:145], v[140:141], v[232:233], v[144:145]
	v_add_f32 v146, v144, v145
	s_nop 1
	v_add_f32_dpp v146, v146, v146 quad_perm:[1,0,3,2] row_mask:0xf bank_mask:0xf bound_ctrl:1
	v_pk_mul_f32 v[224:225], v[138:139], v[224:225]
	v_pk_fma_f32 v[224:225], v[140:141], v[226:227], v[224:225]
	v_add_f32_dpp v146, v146, v146 quad_perm:[2,3,0,1] row_mask:0xf bank_mask:0xf bound_ctrl:1
	v_add_f32 v162, v224, v225
	v_pk_mul_f32 v[242:243], v[242:243], v[250:251] op_sel_hi:[1,0]
	v_add_f32_dpp v146, v146, v146 row_half_mirror row_mask:0xf bank_mask:0xf bound_ctrl:1
	v_pk_mul_f32 v[244:245], v[244:245], v[250:251] op_sel_hi:[1,0]
	s_nop 0
	v_add_f32_dpp v146, v146, v146 row_mirror row_mask:0xf bank_mask:0xf bound_ctrl:1
	v_pk_fma_f32 v[242:243], v[146:147], v[234:235], v[242:243] op_sel_hi:[0,1,1] neg_lo:[1,0,0] neg_hi:[1,0,0]
	v_pk_fma_f32 v[244:245], v[146:147], v[236:237], v[244:245] op_sel_hi:[0,1,1] neg_lo:[1,0,0] neg_hi:[1,0,0]
	v_pk_fma_f32 v[138:139], v[138:139], v[238:239], v[242:243]
	v_pk_fma_f32 v[140:141], v[140:141], v[240:241], v[244:245]
	v_pk_mul_f32 v[246:247], v[138:139], v[246:247]
	v_pk_fma_f32 v[246:247], v[140:141], v[248:249], v[246:247]
	v_add_f32 v163, v246, v247
	s_nop 0
	v_add_f32_dpp v230, v148, v148 row_mirror row_mask:0xf bank_mask:0x3 bound_ctrl:1
	v_add_f32_dpp v230, v156, v156 row_mirror row_mask:0xf bank_mask:0xc bound_ctrl:1
	v_add_f32_dpp v231, v149, v149 row_mirror row_mask:0xf bank_mask:0x3 bound_ctrl:1
	v_add_f32_dpp v231, v157, v157 row_mirror row_mask:0xf bank_mask:0xc bound_ctrl:1
	v_add_f32_dpp v232, v150, v150 row_mirror row_mask:0xf bank_mask:0x3 bound_ctrl:1
	v_add_f32_dpp v232, v158, v158 row_mirror row_mask:0xf bank_mask:0xc bound_ctrl:1
	v_add_f32_dpp v233, v151, v151 row_mirror row_mask:0xf bank_mask:0x3 bound_ctrl:1
	v_add_f32_dpp v233, v159, v159 row_mirror row_mask:0xf bank_mask:0xc bound_ctrl:1
	v_add_f32_dpp v234, v152, v152 row_mirror row_mask:0xf bank_mask:0x3 bound_ctrl:1
	v_add_f32_dpp v234, v160, v160 row_mirror row_mask:0xf bank_mask:0xc bound_ctrl:1
	v_add_f32_dpp v235, v153, v153 row_mirror row_mask:0xf bank_mask:0x3 bound_ctrl:1
	v_add_f32_dpp v235, v161, v161 row_mirror row_mask:0xf bank_mask:0xc bound_ctrl:1
	v_add_f32_dpp v236, v154, v154 row_mirror row_mask:0xf bank_mask:0x3 bound_ctrl:1
	v_add_f32_dpp v236, v162, v162 row_mirror row_mask:0xf bank_mask:0xc bound_ctrl:1
	v_add_f32_dpp v237, v155, v155 row_mirror row_mask:0xf bank_mask:0x3 bound_ctrl:1
	v_add_f32_dpp v237, v163, v163 row_mirror row_mask:0xf bank_mask:0xc bound_ctrl:1
	v_add_f32_dpp v238, v230, v230 row_half_mirror row_mask:0xf bank_mask:0x5 bound_ctrl:1
	v_add_f32_dpp v238, v234, v234 row_half_mirror row_mask:0xf bank_mask:0xa bound_ctrl:1
	v_add_f32_dpp v239, v231, v231 row_half_mirror row_mask:0xf bank_mask:0x5 bound_ctrl:1
	v_add_f32_dpp v239, v235, v235 row_half_mirror row_mask:0xf bank_mask:0xa bound_ctrl:1
	v_add_f32_dpp v240, v232, v232 row_half_mirror row_mask:0xf bank_mask:0x5 bound_ctrl:1
	v_add_f32_dpp v240, v236, v236 row_half_mirror row_mask:0xf bank_mask:0xa bound_ctrl:1
	v_add_f32_dpp v241, v233, v233 row_half_mirror row_mask:0xf bank_mask:0x5 bound_ctrl:1
	v_add_f32_dpp v241, v237, v237 row_half_mirror row_mask:0xf bank_mask:0xa bound_ctrl:1
	s_mov_b32 vcc_lo, 0xcccccccc
	s_mov_b32 vcc_hi, 0xcccccccc
	v_cndmask_b32 v244, v240, v238, vcc
	v_cndmask_b32 v245, v241, v239, vcc
	v_cndmask_b32 v242, v238, v240, vcc
	v_cndmask_b32 v243, v239, v241, vcc
	v_add_f32_dpp v242, v244, v242 quad_perm:[2,3,0,1] row_mask:0xf bank_mask:0xf bound_ctrl:1
	v_add_f32_dpp v243, v245, v243 quad_perm:[2,3,0,1] row_mask:0xf bank_mask:0xf bound_ctrl:1
	s_mov_b32 vcc_lo, 0xaaaaaaaa
	s_mov_b32 vcc_hi, 0xaaaaaaaa
	v_cndmask_b32 v244, v243, v242, vcc
	v_cndmask_b32 v245, v242, v243, vcc
	s_nop 0
	v_add_f32_dpp v19, v244, v245 quad_perm:[1,0,3,2] row_mask:0xf bank_mask:0xf bound_ctrl:1

; #define SCAN_BAR() asm volatile("s_barrier" ::: "memory")
; __device__ __forceinline__ void scan_unit(const Ctx& C0, const float* scn, int T, int quarter, const float* S0, float* Sout, unsigned char* obase, int mode) {
;     ...
;             if (mode == 0) { *(float*)(obase + (size_t)(k * 32 + q) * UPITCH_B + rl * 4) = osel0; *(float*)(obase + (size_t)(k * 32 + 16 + q) * UPITCH_B + rl * 4) = osel1; }
;             SCAN_BAR();
;         }
;         if (mode == 0) *(f32x4*)(Sout + irow * 64 + 4 * q) = (f32x4){S0x, S1x, S2x, S3x};
	s_addc_u32 s1, s1, 0
	v_add_co_u32_e32 v16, vcc, s8, v14
	s_cmp_lg_u32 s0, 0x5600000
	s_nop 0
	v_addc_co_u32_e32 v17, vcc, 0, v15, vcc
	v_add_co_u32_e32 v14, vcc, 0xfcaa000, v14
	global_store_dword v[16:17], v18, off offset:768
	s_nop 0
	v_addc_co_u32_e32 v15, vcc, 0, v15, vcc
	global_store_dword v[14:15], v19, off offset:768
	s_barrier
	s_cbranch_scc1 .LBB0_685
	v_mov_b32_e32 v2, v138
	v_mov_b32_e32 v13, v139
	v_mov_b32_e32 v12, v140
	v_mov_b32_e32 v8, v141
	v_readlane_b32 s0, v255, 46
	s_add_i32 s0, s3, s0
	s_ashr_i32 s1, s0, 31
	s_lshl_b64 s[0:1], s[0:1], 17
	v_readlane_b32 s3, v253, 26
	s_add_u32 s0, s3, s0
	v_readlane_b32 s3, v253, 27
	s_addc_u32 s1, s3, s1
	s_lshl_b32 s2, s2, 14
	s_add_u32 s0, s0, s2
	s_addc_u32 s1, s1, 0
	v_lshlrev_b32_e32 v0, 8, v0
	v_lshl_add_u64 v[6:7], s[0:1], 0, v[0:1]
	v_mov_b32_e32 v5, v1
	v_lshl_add_u64 v[6:7], v[6:7], 0, v[4:5]
	v_mov_b32_e32 v3, v13
	v_mov_b32_e32 v4, v12
	v_mov_b32_e32 v5, v8
	global_store_dwordx4 v[6:7], v[2:5], off
